# deferred routine: software-pipelined transposes with balanced item deal (next item's loads in flight), write-through stores, no write-back
# baseline (speedup 1.0000x reference)
; #define LAS __attribute__((address_space(3)))
; __device__ __forceinline__ void tr_item(const float* W, int ldw, int K, int k0, int sc0, bf16* WT, int dr0, const float* gain, float cs, LAS float* scr, int lane) {
; #pragma unroll 16
;     for (int i = 0; i < 32; ++i) { const int kk = 2 * i + (lane >> 5); const float g = gain ? gain[k0 + kk] * cs : cs;
;         scr[kk * 33 + (lane & 31)] = W[(size_t)(k0 + kk) * ldw + sc0 + (lane & 31)] * g; }
; __global__ void __launch_bounds__(NTHR, 2) hybrid_fwd(Args args) {
;     ...
;         for (int it = gw; it < NIT; it += NGW) {
;             int r = it;
;             if (r < I0) { const int kb = r / 128, nb = r % 128, n0 = 32 * nb; tr_item(w_in, INC, 1024, 64 * kb, n0 < 2048 ? n0 : n0 + 8, W1t, n0, norm_mix_g, 1.0f, scr, lane); continue; } r -= I0;
;             if (r < I1) { const int kb = r / 32, nb = r % 32; tr_item(w_fox_out, 1024, 1024, 64 * kb, 32 * nb, Wmix + 512, 32 * nb, nullptr, 1.0f, scr, lane); continue; } r -= I1;
;             if (r < I2) { const int kb = r / 32, nb = r % 32; tr_item(w_out, 1024, 1024, 64 * kb, 32 * nb, Wout, 32 * nb, nullptr, 1.0f, scr, lane); continue; } r -= I2;
;             if (r < I3) { const int kb = r / 16, nb = r % 16; tr_item(w_xq, 512, 1024, 64 * kb, 32 * nb, Wxq, 32 * nb, norm_x_g, 0.08838834764831845f * LOG2E, scr, lane); continue; } r -= I3;
;             if (r < I4) { const int kb = r / 32, nb = r % 32; tr_item(w_xkv, 1024, 1024, 64 * kb, 32 * nb, Wxkv, 32 * nb, norm_mem_g, 1.0f, scr, lane); continue; } r -= I4;
;             if (r < I5) { const int kb = r / 32, nb = r % 32; tr_item(w_xo, 1024, 512, 64 * kb, 32 * nb, Wxo, 32 * nb, nullptr, 1.0f, scr, lane); continue; } r -= I5;
;             if (r < I6) { const int kb = r / 176, nb = r % 176, n0 = 32 * nb, j = n0 >> 8, wi = n0 & 255; const int sc = wi < 128 ? 128 * j + wi : DFF + 128 * j + (wi - 128);
;                           tr_item(w_ffn_in, 2 * DFF, 1024, 64 * kb, sc, Wffi, n0, norm_ffn_g, 1.0f, scr, lane); continue; } r -= I6;
;             { const int kb = r / 32, nb = r % 32; tr_item(w_ffn_out, 1024, DFF, 64 * kb, 32 * nb, Wffo, 32 * nb, nullptr, 1.0f, scr, lane); }
.LBB0_349:
	s_cmp_lg_u32 s20, 0x100
	s_cbranch_scc1 .Ldef_skip
	s_cmp_lt_u32 s2, 64
	s_cbranch_scc1 .Ldef_skip
	v_lshrrev_b32_e32 v80, 5, v212
	v_and_b32_e32 v81, 31, v212
	v_lshlrev_b32_e32 v81, 2, v81
	v_and_b32_e32 v82, 7, v212
	v_lshlrev_b32_e32 v85, 5, v82
	v_lshlrev_b32_e32 v82, 4, v82
	v_lshrrev_b32_e32 v83, 3, v212
	s_lshl_b32 s79, s74, 14
	v_mul_u32_u24_e32 v86, 0x84, v80
	v_add3_u32 v86, v86, v81, s79
	v_and_b32_e32 v87, 7, v212
	v_mul_u32_u24_e32 v87, 0x420, v87
	v_lshl_add_u32 v87, v83, 2, v87
	v_add_u32_e32 v87, s79, v87
	s_sub_i32 s78, s2, 64
	s_lshl_b32 s78, s78, 3
	s_add_i32 s78, s78, s74
	s_mov_b32 s77, s78
	s_mov_b32 s90, 1
	s_cmp_ge_u32 s77, 256
	s_cbranch_scc1 .Ld2_m1_1
	s_sub_i32 s8, s77, 0
	s_load_dwordx2 s[10:11], s[0:1], 0x48
	s_mov_b32 s24, 0
	s_mov_b32 s14, 0x1000
	s_mov_b32 s26, 0x800
	s_mov_b32 s25, 0x3f800000
	s_add_u32 s28, s18, 0x900400
	s_addc_u32 s29, s19, 0
	s_lshr_b32 s30, s8, 5
	s_and_b32 s31, s8, 31
	s_lshl_b32 s30, s30, 6
	s_lshl_b32 s31, s31, 5
	s_mov_b32 s32, s31
	s_branch .Ld2_dec_1
.Ld2_m1_1:
	s_cmp_ge_u32 s77, 768
	s_cbranch_scc1 .Ld2_m2_1
	s_sub_i32 s8, s77, 256
	s_load_dwordx2 s[10:11], s[0:1], 0x50
	s_mov_b32 s24, 0
	s_mov_b32 s14, 0x1000
	s_mov_b32 s26, 0x800
	s_mov_b32 s25, 0x3f800000
	s_add_u32 s28, s18, 0xb00000
	s_addc_u32 s29, s19, 0
	s_lshr_b32 s30, s8, 5
	s_and_b32 s31, s8, 31
	s_lshl_b32 s30, s30, 6
	s_lshl_b32 s31, s31, 5
	s_mov_b32 s32, s31
	s_branch .Ld2_dec_1
.Ld2_m2_1:
	s_cmp_ge_u32 s77, 1024
	s_cbranch_scc1 .Ld2_m3_1
	s_sub_i32 s8, s77, 768
	s_load_dwordx2 s[10:11], s[0:1], 0x68
	s_load_dwordx2 s[12:13], s[0:1], 0x58
	s_mov_b32 s24, 1
	s_mov_b32 s14, 0x800
	s_mov_b32 s26, 0x800
	s_mov_b32 s25, 0x3e0293ee
	s_add_u32 s28, s18, 0xd00000
	s_addc_u32 s29, s19, 0
	s_lshr_b32 s30, s8, 4
	s_and_b32 s31, s8, 15
	s_lshl_b32 s30, s30, 6
	s_lshl_b32 s31, s31, 5
	s_mov_b32 s32, s31
	s_branch .Ld2_dec_1
.Ld2_m3_1:
	s_cmp_ge_u32 s77, 1280
	s_cbranch_scc1 .Ld2_m4_1
	s_sub_i32 s8, s77, 1024
	s_load_dwordx2 s[10:11], s[0:1], 0x78
	s_mov_b32 s24, 0
	s_mov_b32 s14, 0x1000
	s_mov_b32 s26, 0x400
	s_mov_b32 s25, 0x3f800000
	s_add_u32 s28, s18, 0x1000000
	s_addc_u32 s29, s19, 0
	s_lshr_b32 s30, s8, 5
	s_and_b32 s31, s8, 31
	s_lshl_b32 s30, s30, 6
	s_lshl_b32 s31, s31, 5
	s_mov_b32 s32, s31
	s_branch .Ld2_dec_1
.Ld2_m4_1:
	s_cmp_ge_u32 s77, 4096
	s_cbranch_scc1 .Ld2_m5_1
	s_sub_i32 s8, s77, 1280
	s_load_dwordx2 s[10:11], s[0:1], 0x88
	s_load_dwordx2 s[12:13], s[0:1], 0x80
	s_mov_b32 s24, 1
	s_mov_b32 s14, 0x5800
	s_mov_b32 s26, 0x800
	s_mov_b32 s25, 0x3f800000
	s_add_u32 s28, s18, 0x1100000
	s_addc_u32 s29, s19, 0
	s_mul_i32 s30, s8, 0x1746
	s_lshr_b32 s30, s30, 20
	s_mul_i32 s31, s30, 176
	s_sub_i32 s31, s8, s31
	s_lshl_b32 s30, s30, 6
	s_lshl_b32 s31, s31, 5
	s_lshr_b32 s32, s31, 8
	s_lshl_b32 s32, s32, 7
	s_and_b32 s15, s31, 255
	s_add_i32 s32, s32, s15
	s_cmp_ge_u32 s15, 128
	s_cselect_b32 s15, 2688, 0
	s_add_i32 s32, s32, s15
	s_branch .Ld2_dec_1
.Ld2_m5_1:
	s_sub_i32 s8, s77, 4096
	s_load_dwordx2 s[10:11], s[0:1], 0x90
	s_mov_b32 s24, 0
	s_mov_b32 s14, 0x1000
	s_mov_b32 s26, 0x1600
	s_mov_b32 s25, 0x3f800000
	s_add_u32 s28, s18, 0x1c00000
	s_addc_u32 s29, s19, 0
	s_lshr_b32 s30, s8, 5
	s_and_b32 s31, s8, 31
	s_lshl_b32 s30, s30, 6
	s_lshl_b32 s31, s31, 5
	s_mov_b32 s32, s31
.Ld2_dec_1:
	s_mul_i32 s15, s31, s26
	s_lshl_b32 s41, s30, 1
	s_add_u32 s15, s15, s41
	s_add_u32 s28, s28, s15
	s_addc_u32 s29, s29, 0
	s_waitcnt lgkmcnt(0)
	s_mul_i32 s15, s30, s14
	s_lshl_b32 s41, s32, 2
	s_add_u32 s15, s15, s41
	s_add_u32 s82, s10, s15
	s_addc_u32 s83, s11, 0
	s_lshl_b32 s89, s14, 1
	v_mad_u32_u24 v84, v80, s14, v81
	s_lshl_b32 s15, s30, 2
	s_cmp_eq_u32 s24, 0
	s_cselect_b32 s84, s82, s12
	s_cselect_b32 s85, s83, s13
	s_cselect_b32 s15, 0, s15
	s_add_u32 s84, s84, s15
	s_addc_u32 s85, s85, 0
	global_load_dword v0, v84, s[82:83] nt
	s_add_u32 s82, s82, s89
	s_addc_u32 s83, s83, 0
	global_load_dword v1, v84, s[82:83] nt
	s_add_u32 s82, s82, s89
	s_addc_u32 s83, s83, 0
	global_load_dword v2, v84, s[82:83] nt
	s_add_u32 s82, s82, s89
	s_addc_u32 s83, s83, 0
	global_load_dword v3, v84, s[82:83] nt
	s_add_u32 s82, s82, s89
	s_addc_u32 s83, s83, 0
	global_load_dword v4, v84, s[82:83] nt
	s_add_u32 s82, s82, s89
	s_addc_u32 s83, s83, 0
	global_load_dword v5, v84, s[82:83] nt
	s_add_u32 s82, s82, s89
	s_addc_u32 s83, s83, 0
	global_load_dword v6, v84, s[82:83] nt
	s_add_u32 s82, s82, s89
	s_addc_u32 s83, s83, 0
	global_load_dword v7, v84, s[82:83] nt
	s_add_u32 s82, s82, s89
	s_addc_u32 s83, s83, 0
	global_load_dword v8, v84, s[82:83] nt
	s_add_u32 s82, s82, s89
	s_addc_u32 s83, s83, 0
	global_load_dword v9, v84, s[82:83] nt
	s_add_u32 s82, s82, s89
	s_addc_u32 s83, s83, 0
	global_load_dword v10, v84, s[82:83] nt
	s_add_u32 s82, s82, s89
	s_addc_u32 s83, s83, 0
	global_load_dword v11, v84, s[82:83] nt
	s_add_u32 s82, s82, s89
	s_addc_u32 s83, s83, 0
	global_load_dword v12, v84, s[82:83] nt
	s_add_u32 s82, s82, s89
	s_addc_u32 s83, s83, 0
	global_load_dword v13, v84, s[82:83] nt
	s_add_u32 s82, s82, s89
	s_addc_u32 s83, s83, 0
	global_load_dword v14, v84, s[82:83] nt
	s_add_u32 s82, s82, s89
	s_addc_u32 s83, s83, 0
	global_load_dword v15, v84, s[82:83] nt
	s_add_u32 s82, s82, s89
	s_addc_u32 s83, s83, 0
	global_load_dword v16, v84, s[82:83] nt
	s_add_u32 s82, s82, s89
	s_addc_u32 s83, s83, 0
	global_load_dword v17, v84, s[82:83] nt
	s_add_u32 s82, s82, s89
	s_addc_u32 s83, s83, 0
	global_load_dword v18, v84, s[82:83] nt
	s_add_u32 s82, s82, s89
	s_addc_u32 s83, s83, 0
	global_load_dword v19, v84, s[82:83] nt
	s_add_u32 s82, s82, s89
	s_addc_u32 s83, s83, 0
	global_load_dword v20, v84, s[82:83] nt
	s_add_u32 s82, s82, s89
	s_addc_u32 s83, s83, 0
	global_load_dword v21, v84, s[82:83] nt
	s_add_u32 s82, s82, s89
	s_addc_u32 s83, s83, 0
	global_load_dword v22, v84, s[82:83] nt
	s_add_u32 s82, s82, s89
	s_addc_u32 s83, s83, 0
	global_load_dword v23, v84, s[82:83] nt
	s_add_u32 s82, s82, s89
	s_addc_u32 s83, s83, 0
	global_load_dword v24, v84, s[82:83] nt
	s_add_u32 s82, s82, s89
	s_addc_u32 s83, s83, 0
	global_load_dword v25, v84, s[82:83] nt
	s_add_u32 s82, s82, s89
	s_addc_u32 s83, s83, 0
	global_load_dword v26, v84, s[82:83] nt
	s_add_u32 s82, s82, s89
	s_addc_u32 s83, s83, 0
	global_load_dword v27, v84, s[82:83] nt
	s_add_u32 s82, s82, s89
	s_addc_u32 s83, s83, 0
	global_load_dword v28, v84, s[82:83] nt
	s_add_u32 s82, s82, s89
	s_addc_u32 s83, s83, 0
	global_load_dword v29, v84, s[82:83] nt
	s_add_u32 s82, s82, s89
	s_addc_u32 s83, s83, 0
	global_load_dword v30, v84, s[82:83] nt
	s_add_u32 s82, s82, s89
	s_addc_u32 s83, s83, 0
	global_load_dword v31, v84, s[82:83] nt
	global_load_dwordx4 v[64:67], v85, s[84:85]
	global_load_dwordx4 v[68:71], v85, s[84:85] offset:16
; #define LAS __attribute__((address_space(3)))
; __device__ __forceinline__ void tr_item(const float* W, int ldw, int K, int k0, int sc0, bf16* WT, int dr0, const float* gain, float cs, LAS float* scr, int lane) {
; #pragma unroll 16
;     for (int i = 0; i < 32; ++i) { const int kk = 2 * i + (lane >> 5); const float g = gain ? gain[k0 + kk] * cs : cs;
;         scr[kk * 33 + (lane & 31)] = W[(size_t)(k0 + kk) * ldw + sc0 + (lane & 31)] * g; }
; __global__ void __launch_bounds__(NTHR, 2) hybrid_fwd(Args args) {
;     ...
;         for (int it = gw; it < NIT; it += NGW) {
;             int r = it;
;             if (r < I0) { const int kb = r / 128, nb = r % 128, n0 = 32 * nb; tr_item(w_in, INC, 1024, 64 * kb, n0 < 2048 ? n0 : n0 + 8, W1t, n0, norm_mix_g, 1.0f, scr, lane); continue; } r -= I0;
;             if (r < I1) { const int kb = r / 32, nb = r % 32; tr_item(w_fox_out, 1024, 1024, 64 * kb, 32 * nb, Wmix + 512, 32 * nb, nullptr, 1.0f, scr, lane); continue; } r -= I1;
;             if (r < I2) { const int kb = r / 32, nb = r % 32; tr_item(w_out, 1024, 1024, 64 * kb, 32 * nb, Wout, 32 * nb, nullptr, 1.0f, scr, lane); continue; } r -= I2;
;             if (r < I3) { const int kb = r / 16, nb = r % 16; tr_item(w_xq, 512, 1024, 64 * kb, 32 * nb, Wxq, 32 * nb, norm_x_g, 0.08838834764831845f * LOG2E, scr, lane); continue; } r -= I3;
;             if (r < I4) { const int kb = r / 32, nb = r % 32; tr_item(w_xkv, 1024, 1024, 64 * kb, 32 * nb, Wxkv, 32 * nb, norm_mem_g, 1.0f, scr, lane); continue; } r -= I4;
;             if (r < I5) { const int kb = r / 32, nb = r % 32; tr_item(w_xo, 1024, 512, 64 * kb, 32 * nb, Wxo, 32 * nb, nullptr, 1.0f, scr, lane); continue; } r -= I5;
;             if (r < I6) { const int kb = r / 176, nb = r % 176, n0 = 32 * nb, j = n0 >> 8, wi = n0 & 255; const int sc = wi < 128 ? 128 * j + wi : DFF + 128 * j + (wi - 128);
;                           tr_item(w_ffn_in, 2 * DFF, 1024, 64 * kb, sc, Wffi, n0, norm_ffn_g, 1.0f, scr, lane); continue; } r -= I6;
;             { const int kb = r / 32, nb = r % 32; tr_item(w_ffn_out, 1024, DFF, 64 * kb, 32 * nb, Wffo, 32 * nb, nullptr, 1.0f, scr, lane); }
.Ld2_loop:
	s_mov_b32 s91, 0
	s_cmp_lt_u32 s90, 3
	s_cbranch_scc0 .Ld2_nx_late_a
	s_addk_i32 s77, 0x600
	s_mov_b32 s91, 1
	s_branch .Ld2_nx_done_a
.Ld2_nx_late_a:
	s_cmp_lt_u32 s78, 1024
	s_cbranch_scc1 .Ld2_nx_done_a
	s_addk_i32 s77, 0x200
	s_cmp_lt_u32 s77, 5504
	s_cselect_b32 s91, 1, 0
.Ld2_nx_done_a:
	s_add_i32 s90, s90, 1
	s_mov_b32 s92, s91
	s_cmp_eq_u32 s91, 0
	s_cbranch_scc1 .Ld2_lastA
	s_waitcnt vmcnt(29)
	s_cmp_ge_u32 s77, 256
	s_cbranch_scc1 .Ld2_m1_2
	s_sub_i32 s8, s77, 0
	s_load_dwordx2 s[10:11], s[0:1], 0x48
	s_mov_b32 s34, 0
	s_mov_b32 s14, 0x1000
	s_mov_b32 s36, 0x800
	s_mov_b32 s35, 0x3f800000
	s_add_u32 s38, s18, 0x900400
	s_addc_u32 s39, s19, 0
	s_lshr_b32 s30, s8, 5
	s_and_b32 s31, s8, 31
	s_lshl_b32 s30, s30, 6
	s_lshl_b32 s31, s31, 5
	s_mov_b32 s32, s31
	s_branch .Ld2_dec_2
.Ld2_m1_2:
	s_cmp_ge_u32 s77, 768
	s_cbranch_scc1 .Ld2_m2_2
	s_sub_i32 s8, s77, 256
	s_load_dwordx2 s[10:11], s[0:1], 0x50
	s_mov_b32 s34, 0
	s_mov_b32 s14, 0x1000
	s_mov_b32 s36, 0x800
	s_mov_b32 s35, 0x3f800000
	s_add_u32 s38, s18, 0xb00000
	s_addc_u32 s39, s19, 0
	s_lshr_b32 s30, s8, 5
	s_and_b32 s31, s8, 31
	s_lshl_b32 s30, s30, 6
	s_lshl_b32 s31, s31, 5
	s_mov_b32 s32, s31
	s_branch .Ld2_dec_2
.Ld2_m2_2:
	s_cmp_ge_u32 s77, 1024
	s_cbranch_scc1 .Ld2_m3_2
	s_sub_i32 s8, s77, 768
	s_load_dwordx2 s[10:11], s[0:1], 0x68
	s_load_dwordx2 s[12:13], s[0:1], 0x58
	s_mov_b32 s34, 1
	s_mov_b32 s14, 0x800
	s_mov_b32 s36, 0x800
	s_mov_b32 s35, 0x3e0293ee
	s_add_u32 s38, s18, 0xd00000
	s_addc_u32 s39, s19, 0
	s_lshr_b32 s30, s8, 4
	s_and_b32 s31, s8, 15
	s_lshl_b32 s30, s30, 6
	s_lshl_b32 s31, s31, 5
	s_mov_b32 s32, s31
	s_branch .Ld2_dec_2
.Ld2_m3_2:
	s_cmp_ge_u32 s77, 1280
	s_cbranch_scc1 .Ld2_m4_2
	s_sub_i32 s8, s77, 1024
	s_load_dwordx2 s[10:11], s[0:1], 0x78
	s_mov_b32 s34, 0
	s_mov_b32 s14, 0x1000
	s_mov_b32 s36, 0x400
	s_mov_b32 s35, 0x3f800000
	s_add_u32 s38, s18, 0x1000000
	s_addc_u32 s39, s19, 0
	s_lshr_b32 s30, s8, 5
	s_and_b32 s31, s8, 31
	s_lshl_b32 s30, s30, 6
	s_lshl_b32 s31, s31, 5
	s_mov_b32 s32, s31
	s_branch .Ld2_dec_2
.Ld2_m4_2:
	s_cmp_ge_u32 s77, 4096
	s_cbranch_scc1 .Ld2_m5_2
	s_sub_i32 s8, s77, 1280
	s_load_dwordx2 s[10:11], s[0:1], 0x88
	s_load_dwordx2 s[12:13], s[0:1], 0x80
	s_mov_b32 s34, 1
	s_mov_b32 s14, 0x5800
	s_mov_b32 s36, 0x800
	s_mov_b32 s35, 0x3f800000
	s_add_u32 s38, s18, 0x1100000
	s_addc_u32 s39, s19, 0
	s_mul_i32 s30, s8, 0x1746
	s_lshr_b32 s30, s30, 20
	s_mul_i32 s31, s30, 176
	s_sub_i32 s31, s8, s31
	s_lshl_b32 s30, s30, 6
	s_lshl_b32 s31, s31, 5
	s_lshr_b32 s32, s31, 8
	s_lshl_b32 s32, s32, 7
	s_and_b32 s15, s31, 255
	s_add_i32 s32, s32, s15
	s_cmp_ge_u32 s15, 128
	s_cselect_b32 s15, 2688, 0
	s_add_i32 s32, s32, s15
	s_branch .Ld2_dec_2
.Ld2_m5_2:
	s_sub_i32 s8, s77, 4096
	s_load_dwordx2 s[10:11], s[0:1], 0x90
	s_mov_b32 s34, 0
	s_mov_b32 s14, 0x1000
	s_mov_b32 s36, 0x1600
	s_mov_b32 s35, 0x3f800000
	s_add_u32 s38, s18, 0x1c00000
	s_addc_u32 s39, s19, 0
	s_lshr_b32 s30, s8, 5
	s_and_b32 s31, s8, 31
	s_lshl_b32 s30, s30, 6
	s_lshl_b32 s31, s31, 5
	s_mov_b32 s32, s31
.Ld2_dec_2:
	s_mul_i32 s15, s31, s36
	s_lshl_b32 s41, s30, 1
	s_add_u32 s15, s15, s41
	s_add_u32 s38, s38, s15
	s_addc_u32 s39, s39, 0
	s_waitcnt lgkmcnt(0)
	s_mul_i32 s15, s30, s14
	s_lshl_b32 s41, s32, 2
	s_add_u32 s15, s15, s41
	s_add_u32 s82, s10, s15
	s_addc_u32 s83, s11, 0
	s_lshl_b32 s89, s14, 1
	v_mad_u32_u24 v84, v80, s14, v81
	s_lshl_b32 s15, s30, 2
	s_cmp_eq_u32 s34, 0
	s_cselect_b32 s84, s82, s12
	s_cselect_b32 s85, s83, s13
	s_cselect_b32 s15, 0, s15
	s_add_u32 s84, s84, s15
	s_addc_u32 s85, s85, 0
	global_load_dword v32, v84, s[82:83] nt
	s_add_u32 s82, s82, s89
	s_addc_u32 s83, s83, 0
	global_load_dword v33, v84, s[82:83] nt
	s_add_u32 s82, s82, s89
	s_addc_u32 s83, s83, 0
	global_load_dword v34, v84, s[82:83] nt
	s_add_u32 s82, s82, s89
	s_addc_u32 s83, s83, 0
	global_load_dword v35, v84, s[82:83] nt
	s_add_u32 s82, s82, s89
	s_addc_u32 s83, s83, 0
	global_load_dword v36, v84, s[82:83] nt
	s_add_u32 s82, s82, s89
	s_addc_u32 s83, s83, 0
	global_load_dword v37, v84, s[82:83] nt
	s_add_u32 s82, s82, s89
	s_addc_u32 s83, s83, 0
	global_load_dword v38, v84, s[82:83] nt
	s_add_u32 s82, s82, s89
	s_addc_u32 s83, s83, 0
	global_load_dword v39, v84, s[82:83] nt
	s_add_u32 s82, s82, s89
	s_addc_u32 s83, s83, 0
	global_load_dword v40, v84, s[82:83] nt
	s_add_u32 s82, s82, s89
	s_addc_u32 s83, s83, 0
	global_load_dword v41, v84, s[82:83] nt
	s_add_u32 s82, s82, s89
	s_addc_u32 s83, s83, 0
	global_load_dword v42, v84, s[82:83] nt
	s_add_u32 s82, s82, s89
	s_addc_u32 s83, s83, 0
	global_load_dword v43, v84, s[82:83] nt
	s_add_u32 s82, s82, s89
	s_addc_u32 s83, s83, 0
	global_load_dword v44, v84, s[82:83] nt
	s_add_u32 s82, s82, s89
	s_addc_u32 s83, s83, 0
	global_load_dword v45, v84, s[82:83] nt
	s_add_u32 s82, s82, s89
	s_addc_u32 s83, s83, 0
	global_load_dword v46, v84, s[82:83] nt
	s_add_u32 s82, s82, s89
	s_addc_u32 s83, s83, 0
	global_load_dword v47, v84, s[82:83] nt
	s_add_u32 s82, s82, s89
	s_addc_u32 s83, s83, 0
	global_load_dword v48, v84, s[82:83] nt
	s_add_u32 s82, s82, s89
	s_addc_u32 s83, s83, 0
	global_load_dword v49, v84, s[82:83] nt
	s_add_u32 s82, s82, s89
	s_addc_u32 s83, s83, 0
	global_load_dword v50, v84, s[82:83] nt
	s_add_u32 s82, s82, s89
	s_addc_u32 s83, s83, 0
	global_load_dword v51, v84, s[82:83] nt
	s_add_u32 s82, s82, s89
	s_addc_u32 s83, s83, 0
	global_load_dword v52, v84, s[82:83] nt
	s_add_u32 s82, s82, s89
	s_addc_u32 s83, s83, 0
	global_load_dword v53, v84, s[82:83] nt
	s_add_u32 s82, s82, s89
	s_addc_u32 s83, s83, 0
	global_load_dword v54, v84, s[82:83] nt
	s_add_u32 s82, s82, s89
	s_addc_u32 s83, s83, 0
	global_load_dword v55, v84, s[82:83] nt
	s_add_u32 s82, s82, s89
	s_addc_u32 s83, s83, 0
	global_load_dword v56, v84, s[82:83] nt
	s_add_u32 s82, s82, s89
	s_addc_u32 s83, s83, 0
	global_load_dword v57, v84, s[82:83] nt
	s_add_u32 s82, s82, s89
	s_addc_u32 s83, s83, 0
	global_load_dword v58, v84, s[82:83] nt
	s_add_u32 s82, s82, s89
	s_addc_u32 s83, s83, 0
	global_load_dword v59, v84, s[82:83] nt
	s_add_u32 s82, s82, s89
	s_addc_u32 s83, s83, 0
	global_load_dword v60, v84, s[82:83] nt
	s_add_u32 s82, s82, s89
	s_addc_u32 s83, s83, 0
	global_load_dword v61, v84, s[82:83] nt
	s_add_u32 s82, s82, s89
	s_addc_u32 s83, s83, 0
	global_load_dword v62, v84, s[82:83] nt
	s_add_u32 s82, s82, s89
	s_addc_u32 s83, s83, 0
	global_load_dword v63, v84, s[82:83] nt
	global_load_dwordx4 v[72:75], v85, s[84:85]
	global_load_dwordx4 v[76:79], v85, s[84:85] offset:16
	s_waitcnt vmcnt(34)
	s_branch .Ld2_procA

; #define LAS __attribute__((address_space(3)))
; __device__ __forceinline__ unsigned pk2(float lo, float hi) { return pg8::cvt_pk_bf16(lo, hi); }
; __device__ __forceinline__ void tr_item(const float* W, int ldw, int K, int k0, int sc0, bf16* WT, int dr0, const float* gain, float cs, LAS float* scr, int lane) {
; #pragma unroll 16
;     for (int i = 0; i < 32; ++i) { const int kk = 2 * i + (lane >> 5); const float g = gain ? gain[k0 + kk] * cs : cs;
;         scr[kk * 33 + (lane & 31)] = W[(size_t)(k0 + kk) * ldw + sc0 + (lane & 31)] * g; }
;     asm volatile("s_waitcnt lgkmcnt(0)" ::: "memory");
;     const int c = lane & 7;
; #pragma unroll
;     for (int j = 0; j < 4; ++j) { const int n = (lane >> 3) + 8 * j; const LAS float* s = scr + (8 * c) * 33 + n;
;         u32x4 o; o.x = pk2(s[0 * 33], s[1 * 33]); o.y = pk2(s[2 * 33], s[3 * 33]); o.z = pk2(s[4 * 33], s[5 * 33]); o.w = pk2(s[6 * 33], s[7 * 33]);
;         *(u32x4*)(WT + (size_t)(dr0 + n) * K + k0 + 8 * c) = o; }
;     asm volatile("s_waitcnt lgkmcnt(0)" ::: "memory");
; }
.Ld2_procA:
	s_cmp_eq_u32 s24, 0
	s_cbranch_scc1 .Ld2_ng_3
	v_mul_f32_e32 v64, s25, v64
	v_mul_f32_e32 v65, s25, v65
	v_mul_f32_e32 v66, s25, v66
	v_mul_f32_e32 v67, s25, v67
	v_mul_f32_e32 v68, s25, v68
	v_mul_f32_e32 v69, s25, v69
	v_mul_f32_e32 v70, s25, v70
	v_mul_f32_e32 v71, s25, v71
	s_branch .Ld2_gd_3
.Ld2_ng_3:
	v_mov_b32_e32 v64, s25
	v_mov_b32_e32 v65, s25
	v_mov_b32_e32 v66, s25
	v_mov_b32_e32 v67, s25
	v_mov_b32_e32 v68, s25
	v_mov_b32_e32 v69, s25
	v_mov_b32_e32 v70, s25
	v_mov_b32_e32 v71, s25
.Ld2_gd_3:
	ds_write_b32 v86, v0 offset:0
	ds_write_b32 v86, v1 offset:264
	ds_write_b32 v86, v2 offset:528
	ds_write_b32 v86, v3 offset:792
	ds_write_b32 v86, v4 offset:1056
	ds_write_b32 v86, v5 offset:1320
	ds_write_b32 v86, v6 offset:1584
	ds_write_b32 v86, v7 offset:1848
	ds_write_b32 v86, v8 offset:2112
	ds_write_b32 v86, v9 offset:2376
	ds_write_b32 v86, v10 offset:2640
	ds_write_b32 v86, v11 offset:2904
	ds_write_b32 v86, v12 offset:3168
	ds_write_b32 v86, v13 offset:3432
	ds_write_b32 v86, v14 offset:3696
	ds_write_b32 v86, v15 offset:3960
	ds_write_b32 v86, v16 offset:4224
	ds_write_b32 v86, v17 offset:4488
	ds_write_b32 v86, v18 offset:4752
	ds_write_b32 v86, v19 offset:5016
	ds_write_b32 v86, v20 offset:5280
	ds_write_b32 v86, v21 offset:5544
	ds_write_b32 v86, v22 offset:5808
	ds_write_b32 v86, v23 offset:6072
	ds_write_b32 v86, v24 offset:6336
	ds_write_b32 v86, v25 offset:6600
	ds_write_b32 v86, v26 offset:6864
	ds_write_b32 v86, v27 offset:7128
	ds_write_b32 v86, v28 offset:7392
	ds_write_b32 v86, v29 offset:7656
	ds_write_b32 v86, v30 offset:7920
	ds_write_b32 v86, v31 offset:8184
	v_mad_u32_u24 v88, v83, s26, v82
	s_lshl_b32 s42, s26, 3
	s_waitcnt lgkmcnt(0)
	ds_read2_b32 v[96:97], v87 offset0:0 offset1:33
	ds_read2_b32 v[98:99], v87 offset0:66 offset1:99
	ds_read2_b32 v[100:101], v87 offset0:132 offset1:165
	ds_read2_b32 v[102:103], v87 offset0:198 offset1:231
	s_waitcnt lgkmcnt(0)
	v_mul_f32_e32 v96, v96, v64
	v_mul_f32_e32 v97, v97, v65
	v_mul_f32_e32 v98, v98, v66
	v_mul_f32_e32 v99, v99, v67
	v_mul_f32_e32 v100, v100, v68
	v_mul_f32_e32 v101, v101, v69
	v_mul_f32_e32 v102, v102, v70
	v_mul_f32_e32 v103, v103, v71
	v_cvt_pk_bf16_f32 v104, v96, v97
	v_cvt_pk_bf16_f32 v105, v98, v99
	v_cvt_pk_bf16_f32 v106, v100, v101
	v_cvt_pk_bf16_f32 v107, v102, v103
	global_store_dwordx4 v88, v[104:107], s[28:29] sc1
	s_add_u32 s28, s28, s42
	s_addc_u32 s29, s29, 0
	s_nop 1
	ds_read2_b32 v[96:97], v87 offset0:8 offset1:41
	ds_read2_b32 v[98:99], v87 offset0:74 offset1:107
	ds_read2_b32 v[100:101], v87 offset0:140 offset1:173
	ds_read2_b32 v[102:103], v87 offset0:206 offset1:239
	s_waitcnt lgkmcnt(0)
	v_mul_f32_e32 v96, v96, v64
	v_mul_f32_e32 v97, v97, v65
	v_mul_f32_e32 v98, v98, v66
	v_mul_f32_e32 v99, v99, v67
	v_mul_f32_e32 v100, v100, v68
	v_mul_f32_e32 v101, v101, v69
	v_mul_f32_e32 v102, v102, v70
	v_mul_f32_e32 v103, v103, v71
	v_cvt_pk_bf16_f32 v104, v96, v97
	v_cvt_pk_bf16_f32 v105, v98, v99
	v_cvt_pk_bf16_f32 v106, v100, v101
	v_cvt_pk_bf16_f32 v107, v102, v103
	global_store_dwordx4 v88, v[104:107], s[28:29] sc1
	s_add_u32 s28, s28, s42
	s_addc_u32 s29, s29, 0
	s_nop 1
	ds_read2_b32 v[96:97], v87 offset0:16 offset1:49
	ds_read2_b32 v[98:99], v87 offset0:82 offset1:115
	ds_read2_b32 v[100:101], v87 offset0:148 offset1:181
	ds_read2_b32 v[102:103], v87 offset0:214 offset1:247
	s_waitcnt lgkmcnt(0)
	v_mul_f32_e32 v96, v96, v64
	v_mul_f32_e32 v97, v97, v65
	v_mul_f32_e32 v98, v98, v66
	v_mul_f32_e32 v99, v99, v67
	v_mul_f32_e32 v100, v100, v68
	v_mul_f32_e32 v101, v101, v69
	v_mul_f32_e32 v102, v102, v70
	v_mul_f32_e32 v103, v103, v71
	v_cvt_pk_bf16_f32 v104, v96, v97
	v_cvt_pk_bf16_f32 v105, v98, v99
	v_cvt_pk_bf16_f32 v106, v100, v101
	v_cvt_pk_bf16_f32 v107, v102, v103
	global_store_dwordx4 v88, v[104:107], s[28:29] sc1
	s_add_u32 s28, s28, s42
	s_addc_u32 s29, s29, 0
	s_nop 1
	ds_read2_b32 v[96:97], v87 offset0:24 offset1:57
	ds_read2_b32 v[98:99], v87 offset0:90 offset1:123
	ds_read2_b32 v[100:101], v87 offset0:156 offset1:189
	ds_read2_b32 v[102:103], v87 offset0:222 offset1:255
	s_waitcnt lgkmcnt(0)
	v_mul_f32_e32 v96, v96, v64
	v_mul_f32_e32 v97, v97, v65
	v_mul_f32_e32 v98, v98, v66
	v_mul_f32_e32 v99, v99, v67
	v_mul_f32_e32 v100, v100, v68
	v_mul_f32_e32 v101, v101, v69
	v_mul_f32_e32 v102, v102, v70
	v_mul_f32_e32 v103, v103, v71
	v_cvt_pk_bf16_f32 v104, v96, v97
	v_cvt_pk_bf16_f32 v105, v98, v99
	v_cvt_pk_bf16_f32 v106, v100, v101
	v_cvt_pk_bf16_f32 v107, v102, v103
	global_store_dwordx4 v88, v[104:107], s[28:29] sc1
	s_cmp_eq_u32 s92, 0
	s_cbranch_scc1 .Ld2_items_done
	s_mov_b32 s91, 0
	s_cmp_lt_u32 s90, 3
	s_cbranch_scc0 .Ld2_nx_late_b
	s_addk_i32 s77, 0x600
	s_mov_b32 s91, 1
	s_branch .Ld2_nx_done_b

; __global__ void __launch_bounds__(NTHR, 2) hybrid_fwd(Args args) {
;     ...
;         for (int it = gw; it < NIT; it += NGW) {
;             int r = it;
;             if (r < I0) { const int kb = r / 128, nb = r % 128, n0 = 32 * nb; tr_item(w_in, INC, 1024, 64 * kb, n0 < 2048 ? n0 : n0 + 8, W1t, n0, norm_mix_g, 1.0f, scr, lane); continue; } r -= I0;
;             if (r < I1) { const int kb = r / 32, nb = r % 32; tr_item(w_fox_out, 1024, 1024, 64 * kb, 32 * nb, Wmix + 512, 32 * nb, nullptr, 1.0f, scr, lane); continue; } r -= I1;
.Ld2_nx_done_b:
	s_add_i32 s90, s90, 1
	s_mov_b32 s92, s91
	s_cmp_eq_u32 s91, 0
	s_cbranch_scc1 .Ld2_lastB
	s_waitcnt vmcnt(29)
	s_cmp_ge_u32 s77, 256
	s_cbranch_scc1 .Ld2_m1_4
	s_sub_i32 s8, s77, 0
	s_load_dwordx2 s[10:11], s[0:1], 0x48
	s_mov_b32 s24, 0
	s_mov_b32 s14, 0x1000
	s_mov_b32 s26, 0x800
	s_mov_b32 s25, 0x3f800000
	s_add_u32 s28, s18, 0x900400
	s_addc_u32 s29, s19, 0
	s_lshr_b32 s30, s8, 5
	s_and_b32 s31, s8, 31
	s_lshl_b32 s30, s30, 6
	s_lshl_b32 s31, s31, 5
	s_mov_b32 s32, s31
	s_branch .Ld2_dec_4

; #define LAS __attribute__((address_space(3)))
; __device__ __forceinline__ void tr_item(const float* W, int ldw, int K, int k0, int sc0, bf16* WT, int dr0, const float* gain, float cs, LAS float* scr, int lane) {
; #pragma unroll 16
;     for (int i = 0; i < 32; ++i) { const int kk = 2 * i + (lane >> 5); const float g = gain ? gain[k0 + kk] * cs : cs;
;         scr[kk * 33 + (lane & 31)] = W[(size_t)(k0 + kk) * ldw + sc0 + (lane & 31)] * g; }
.Ld2_dec_4:
	s_mul_i32 s15, s31, s26
	s_lshl_b32 s41, s30, 1
	s_add_u32 s15, s15, s41
	s_add_u32 s28, s28, s15
	s_addc_u32 s29, s29, 0
	s_waitcnt lgkmcnt(0)
	s_mul_i32 s15, s30, s14
	s_lshl_b32 s41, s32, 2
	s_add_u32 s15, s15, s41
	s_add_u32 s82, s10, s15
	s_addc_u32 s83, s11, 0
	s_lshl_b32 s89, s14, 1
	v_mad_u32_u24 v84, v80, s14, v81
	s_lshl_b32 s15, s30, 2
	s_cmp_eq_u32 s24, 0
	s_cselect_b32 s84, s82, s12
	s_cselect_b32 s85, s83, s13
	s_cselect_b32 s15, 0, s15
	s_add_u32 s84, s84, s15
	s_addc_u32 s85, s85, 0
	global_load_dword v0, v84, s[82:83] nt
	s_add_u32 s82, s82, s89
	s_addc_u32 s83, s83, 0
	global_load_dword v1, v84, s[82:83] nt
	s_add_u32 s82, s82, s89
	s_addc_u32 s83, s83, 0
	global_load_dword v2, v84, s[82:83] nt
	s_add_u32 s82, s82, s89
	s_addc_u32 s83, s83, 0
	global_load_dword v3, v84, s[82:83] nt
	s_add_u32 s82, s82, s89
	s_addc_u32 s83, s83, 0
	global_load_dword v4, v84, s[82:83] nt
	s_add_u32 s82, s82, s89
	s_addc_u32 s83, s83, 0
	global_load_dword v5, v84, s[82:83] nt
	s_add_u32 s82, s82, s89
	s_addc_u32 s83, s83, 0
	global_load_dword v6, v84, s[82:83] nt
	s_add_u32 s82, s82, s89
	s_addc_u32 s83, s83, 0
	global_load_dword v7, v84, s[82:83] nt
	s_add_u32 s82, s82, s89
	s_addc_u32 s83, s83, 0
	global_load_dword v8, v84, s[82:83] nt
	s_add_u32 s82, s82, s89
	s_addc_u32 s83, s83, 0
	global_load_dword v9, v84, s[82:83] nt
	s_add_u32 s82, s82, s89
	s_addc_u32 s83, s83, 0
	global_load_dword v10, v84, s[82:83] nt
	s_add_u32 s82, s82, s89
	s_addc_u32 s83, s83, 0
	global_load_dword v11, v84, s[82:83] nt
	s_add_u32 s82, s82, s89
	s_addc_u32 s83, s83, 0
	global_load_dword v12, v84, s[82:83] nt
	s_add_u32 s82, s82, s89
	s_addc_u32 s83, s83, 0
	global_load_dword v13, v84, s[82:83] nt
	s_add_u32 s82, s82, s89
	s_addc_u32 s83, s83, 0
	global_load_dword v14, v84, s[82:83] nt
	s_add_u32 s82, s82, s89
	s_addc_u32 s83, s83, 0
	global_load_dword v15, v84, s[82:83] nt
	s_add_u32 s82, s82, s89
	s_addc_u32 s83, s83, 0
	global_load_dword v16, v84, s[82:83] nt
	s_add_u32 s82, s82, s89
	s_addc_u32 s83, s83, 0
	global_load_dword v17, v84, s[82:83] nt
	s_add_u32 s82, s82, s89
	s_addc_u32 s83, s83, 0
	global_load_dword v18, v84, s[82:83] nt
	s_add_u32 s82, s82, s89
	s_addc_u32 s83, s83, 0
	global_load_dword v19, v84, s[82:83] nt
	s_add_u32 s82, s82, s89
	s_addc_u32 s83, s83, 0
	global_load_dword v20, v84, s[82:83] nt
	s_add_u32 s82, s82, s89
	s_addc_u32 s83, s83, 0
	global_load_dword v21, v84, s[82:83] nt
	s_add_u32 s82, s82, s89
	s_addc_u32 s83, s83, 0
	global_load_dword v22, v84, s[82:83] nt
	s_add_u32 s82, s82, s89
	s_addc_u32 s83, s83, 0
	global_load_dword v23, v84, s[82:83] nt
	s_add_u32 s82, s82, s89
	s_addc_u32 s83, s83, 0
	global_load_dword v24, v84, s[82:83] nt
	s_add_u32 s82, s82, s89
	s_addc_u32 s83, s83, 0
	global_load_dword v25, v84, s[82:83] nt
	s_add_u32 s82, s82, s89
	s_addc_u32 s83, s83, 0
	global_load_dword v26, v84, s[82:83] nt
	s_add_u32 s82, s82, s89
	s_addc_u32 s83, s83, 0
	global_load_dword v27, v84, s[82:83] nt
	s_add_u32 s82, s82, s89
	s_addc_u32 s83, s83, 0
	global_load_dword v28, v84, s[82:83] nt
	s_add_u32 s82, s82, s89
	s_addc_u32 s83, s83, 0
	global_load_dword v29, v84, s[82:83] nt
	s_add_u32 s82, s82, s89
	s_addc_u32 s83, s83, 0
	global_load_dword v30, v84, s[82:83] nt
	s_add_u32 s82, s82, s89
	s_addc_u32 s83, s83, 0
	global_load_dword v31, v84, s[82:83] nt
	global_load_dwordx4 v[64:67], v85, s[84:85]
	global_load_dwordx4 v[68:71], v85, s[84:85] offset:16
	s_waitcnt vmcnt(34)
	s_branch .Ld2_procB

; #define LAS __attribute__((address_space(3)))
; __device__ __forceinline__ unsigned pk2(float lo, float hi) { return pg8::cvt_pk_bf16(lo, hi); }
; __device__ __forceinline__ void tr_item(const float* W, int ldw, int K, int k0, int sc0, bf16* WT, int dr0, const float* gain, float cs, LAS float* scr, int lane) {
; #pragma unroll 16
;     for (int i = 0; i < 32; ++i) { const int kk = 2 * i + (lane >> 5); const float g = gain ? gain[k0 + kk] * cs : cs;
;         scr[kk * 33 + (lane & 31)] = W[(size_t)(k0 + kk) * ldw + sc0 + (lane & 31)] * g; }
;     asm volatile("s_waitcnt lgkmcnt(0)" ::: "memory");
;     const int c = lane & 7;
; #pragma unroll
;     for (int j = 0; j < 4; ++j) { const int n = (lane >> 3) + 8 * j; const LAS float* s = scr + (8 * c) * 33 + n;
;         u32x4 o; o.x = pk2(s[0 * 33], s[1 * 33]); o.y = pk2(s[2 * 33], s[3 * 33]); o.z = pk2(s[4 * 33], s[5 * 33]); o.w = pk2(s[6 * 33], s[7 * 33]);
;         *(u32x4*)(WT + (size_t)(dr0 + n) * K + k0 + 8 * c) = o; }
;     asm volatile("s_waitcnt lgkmcnt(0)" ::: "memory");
; }
.Ld2_procB:
	s_cmp_eq_u32 s34, 0
	s_cbranch_scc1 .Ld2_ng_5
	v_mul_f32_e32 v72, s35, v72
	v_mul_f32_e32 v73, s35, v73
	v_mul_f32_e32 v74, s35, v74
	v_mul_f32_e32 v75, s35, v75
	v_mul_f32_e32 v76, s35, v76
	v_mul_f32_e32 v77, s35, v77
	v_mul_f32_e32 v78, s35, v78
	v_mul_f32_e32 v79, s35, v79
	s_branch .Ld2_gd_5
.Ld2_ng_5:
	v_mov_b32_e32 v72, s35
	v_mov_b32_e32 v73, s35
	v_mov_b32_e32 v74, s35
	v_mov_b32_e32 v75, s35
	v_mov_b32_e32 v76, s35
	v_mov_b32_e32 v77, s35
	v_mov_b32_e32 v78, s35
	v_mov_b32_e32 v79, s35
.Ld2_gd_5:
	ds_write_b32 v86, v32 offset:0
	ds_write_b32 v86, v33 offset:264
	ds_write_b32 v86, v34 offset:528
	ds_write_b32 v86, v35 offset:792
	ds_write_b32 v86, v36 offset:1056
	ds_write_b32 v86, v37 offset:1320
	ds_write_b32 v86, v38 offset:1584
	ds_write_b32 v86, v39 offset:1848
	ds_write_b32 v86, v40 offset:2112
	ds_write_b32 v86, v41 offset:2376
	ds_write_b32 v86, v42 offset:2640
	ds_write_b32 v86, v43 offset:2904
	ds_write_b32 v86, v44 offset:3168
	ds_write_b32 v86, v45 offset:3432
	ds_write_b32 v86, v46 offset:3696
	ds_write_b32 v86, v47 offset:3960
	ds_write_b32 v86, v48 offset:4224
	ds_write_b32 v86, v49 offset:4488
	ds_write_b32 v86, v50 offset:4752
	ds_write_b32 v86, v51 offset:5016
	ds_write_b32 v86, v52 offset:5280
	ds_write_b32 v86, v53 offset:5544
	ds_write_b32 v86, v54 offset:5808
	ds_write_b32 v86, v55 offset:6072
	ds_write_b32 v86, v56 offset:6336
	ds_write_b32 v86, v57 offset:6600
	ds_write_b32 v86, v58 offset:6864
	ds_write_b32 v86, v59 offset:7128
	ds_write_b32 v86, v60 offset:7392
	ds_write_b32 v86, v61 offset:7656
	ds_write_b32 v86, v62 offset:7920
	ds_write_b32 v86, v63 offset:8184
	v_mad_u32_u24 v88, v83, s36, v82
	s_lshl_b32 s42, s36, 3
	s_waitcnt lgkmcnt(0)
	ds_read2_b32 v[96:97], v87 offset0:0 offset1:33
	ds_read2_b32 v[98:99], v87 offset0:66 offset1:99
	ds_read2_b32 v[100:101], v87 offset0:132 offset1:165
	ds_read2_b32 v[102:103], v87 offset0:198 offset1:231
	s_waitcnt lgkmcnt(0)
	v_mul_f32_e32 v96, v96, v72
	v_mul_f32_e32 v97, v97, v73
	v_mul_f32_e32 v98, v98, v74
	v_mul_f32_e32 v99, v99, v75
	v_mul_f32_e32 v100, v100, v76
	v_mul_f32_e32 v101, v101, v77
	v_mul_f32_e32 v102, v102, v78
	v_mul_f32_e32 v103, v103, v79
	v_cvt_pk_bf16_f32 v104, v96, v97
	v_cvt_pk_bf16_f32 v105, v98, v99
	v_cvt_pk_bf16_f32 v106, v100, v101
	v_cvt_pk_bf16_f32 v107, v102, v103
	global_store_dwordx4 v88, v[104:107], s[38:39] sc1
	s_add_u32 s38, s38, s42
	s_addc_u32 s39, s39, 0
	s_nop 1
	ds_read2_b32 v[96:97], v87 offset0:8 offset1:41
	ds_read2_b32 v[98:99], v87 offset0:74 offset1:107
	ds_read2_b32 v[100:101], v87 offset0:140 offset1:173
	ds_read2_b32 v[102:103], v87 offset0:206 offset1:239
	s_waitcnt lgkmcnt(0)
	v_mul_f32_e32 v96, v96, v72
	v_mul_f32_e32 v97, v97, v73
	v_mul_f32_e32 v98, v98, v74
	v_mul_f32_e32 v99, v99, v75
	v_mul_f32_e32 v100, v100, v76
	v_mul_f32_e32 v101, v101, v77
	v_mul_f32_e32 v102, v102, v78
	v_mul_f32_e32 v103, v103, v79
	v_cvt_pk_bf16_f32 v104, v96, v97
	v_cvt_pk_bf16_f32 v105, v98, v99
	v_cvt_pk_bf16_f32 v106, v100, v101
	v_cvt_pk_bf16_f32 v107, v102, v103
	global_store_dwordx4 v88, v[104:107], s[38:39] sc1
	s_add_u32 s38, s38, s42
	s_addc_u32 s39, s39, 0
	s_nop 1
	ds_read2_b32 v[96:97], v87 offset0:16 offset1:49
	ds_read2_b32 v[98:99], v87 offset0:82 offset1:115
	ds_read2_b32 v[100:101], v87 offset0:148 offset1:181
	ds_read2_b32 v[102:103], v87 offset0:214 offset1:247
	s_waitcnt lgkmcnt(0)
	v_mul_f32_e32 v96, v96, v72
	v_mul_f32_e32 v97, v97, v73
	v_mul_f32_e32 v98, v98, v74
	v_mul_f32_e32 v99, v99, v75
	v_mul_f32_e32 v100, v100, v76
	v_mul_f32_e32 v101, v101, v77
	v_mul_f32_e32 v102, v102, v78
	v_mul_f32_e32 v103, v103, v79
	v_cvt_pk_bf16_f32 v104, v96, v97
	v_cvt_pk_bf16_f32 v105, v98, v99
	v_cvt_pk_bf16_f32 v106, v100, v101
	v_cvt_pk_bf16_f32 v107, v102, v103
	global_store_dwordx4 v88, v[104:107], s[38:39] sc1
	s_add_u32 s38, s38, s42
	s_addc_u32 s39, s39, 0
	s_nop 1
	ds_read2_b32 v[96:97], v87 offset0:24 offset1:57
	ds_read2_b32 v[98:99], v87 offset0:90 offset1:123
	ds_read2_b32 v[100:101], v87 offset0:156 offset1:189
	ds_read2_b32 v[102:103], v87 offset0:222 offset1:255
	s_waitcnt lgkmcnt(0)
	v_mul_f32_e32 v96, v96, v72
	v_mul_f32_e32 v97, v97, v73
	v_mul_f32_e32 v98, v98, v74
	v_mul_f32_e32 v99, v99, v75
	v_mul_f32_e32 v100, v100, v76
	v_mul_f32_e32 v101, v101, v77
	v_mul_f32_e32 v102, v102, v78
	v_mul_f32_e32 v103, v103, v79
	v_cvt_pk_bf16_f32 v104, v96, v97
	v_cvt_pk_bf16_f32 v105, v98, v99
	v_cvt_pk_bf16_f32 v106, v100, v101
	v_cvt_pk_bf16_f32 v107, v102, v103
	global_store_dwordx4 v88, v[104:107], s[38:39] sc1
	s_cmp_eq_u32 s92, 0
	s_cbranch_scc0 .Ld2_loop
; __global__ void __launch_bounds__(NTHR, 2) hybrid_fwd(Args args) {
;     ...
;         for (int bi = blk; bi < 128; bi += G) { const int nb = bi >> 3, kl = bi & 7, k0 = kl * 64 + wave * 8, gb = (k0 >> 7) * 128, n = nb * 64 + lane;
;             float a[8];
; #pragma unroll
;             for (int kk = 0; kk < 8; ++kk) a[kk] = 0.f;
; #pragma unroll 8
;             for (int d = 0; d < 128; ++d) { const float wv = w_pool_out[(size_t)(gb + d) * 1024 + n] * pool_scale[gb + d];
; #pragma unroll
;                 for (int kk = 0; kk < 8; ++kk) a[kk] += pool_w[(size_t)(k0 + kk) * 128 + d] * wv; }
.Ld2_items_done:
	s_waitcnt lgkmcnt(0)
	s_cmp_ge_u32 s2, 192
	s_cbranch_scc1 .Ldef_fold_done
	s_load_dwordx2 s[8:9], s[0:1], 0x30
	s_load_dwordx2 s[10:11], s[0:1], 0x38
	s_load_dwordx2 s[12:13], s[0:1], 0x40
	s_sub_i32 s24, s2, 64
	s_lshr_b32 s25, s24, 3
	s_and_b32 s26, s24, 7
	s_lshl_b32 s27, s26, 6
	s_lshl_b32 s79, s74, 3
	s_add_i32 s27, s27, s79
	s_and_b32 s28, s27, 0xffffff80
	s_lshl_b32 s29, s25, 6
	v_add_u32_e32 v155, s29, v212
	v_lshlrev_b32_e32 v156, 2, v155
	v_lshlrev_b32_e32 v157, 2, v212
	s_waitcnt lgkmcnt(0)
	s_lshl_b32 s79, s28, 12
	s_add_u32 s82, s12, s79
	s_addc_u32 s83, s13, 0
	global_load_dword v0, v156, s[82:83] nt
	s_add_u32 s82, s82, 0x1000
	s_addc_u32 s83, s83, 0
	global_load_dword v1, v156, s[82:83] nt
	s_add_u32 s82, s82, 0x1000
	s_addc_u32 s83, s83, 0
	global_load_dword v2, v156, s[82:83] nt
	s_add_u32 s82, s82, 0x1000
	s_addc_u32 s83, s83, 0
	global_load_dword v3, v156, s[82:83] nt
	s_add_u32 s82, s82, 0x1000
	s_addc_u32 s83, s83, 0
	global_load_dword v4, v156, s[82:83] nt
	s_add_u32 s82, s82, 0x1000
	s_addc_u32 s83, s83, 0
	global_load_dword v5, v156, s[82:83] nt
	s_add_u32 s82, s82, 0x1000
	s_addc_u32 s83, s83, 0
	global_load_dword v6, v156, s[82:83] nt
	s_add_u32 s82, s82, 0x1000
	s_addc_u32 s83, s83, 0
	global_load_dword v7, v156, s[82:83] nt
	s_add_u32 s82, s82, 0x1000
	s_addc_u32 s83, s83, 0
	global_load_dword v8, v156, s[82:83] nt
	s_add_u32 s82, s82, 0x1000
	s_addc_u32 s83, s83, 0
	global_load_dword v9, v156, s[82:83] nt
	s_add_u32 s82, s82, 0x1000
	s_addc_u32 s83, s83, 0
	global_load_dword v10, v156, s[82:83] nt
	s_add_u32 s82, s82, 0x1000
	s_addc_u32 s83, s83, 0
	global_load_dword v11, v156, s[82:83] nt
	s_add_u32 s82, s82, 0x1000
	s_addc_u32 s83, s83, 0
	global_load_dword v12, v156, s[82:83] nt
	s_add_u32 s82, s82, 0x1000
	s_addc_u32 s83, s83, 0
	global_load_dword v13, v156, s[82:83] nt
	s_add_u32 s82, s82, 0x1000
	s_addc_u32 s83, s83, 0
	global_load_dword v14, v156, s[82:83] nt
	s_add_u32 s82, s82, 0x1000
	s_addc_u32 s83, s83, 0
	global_load_dword v15, v156, s[82:83] nt
	s_add_u32 s82, s82, 0x1000
	s_addc_u32 s83, s83, 0
	global_load_dword v16, v156, s[82:83] nt
	s_add_u32 s82, s82, 0x1000
	s_addc_u32 s83, s83, 0
	global_load_dword v17, v156, s[82:83] nt
	s_add_u32 s82, s82, 0x1000
	s_addc_u32 s83, s83, 0
	global_load_dword v18, v156, s[82:83] nt
	s_add_u32 s82, s82, 0x1000
	s_addc_u32 s83, s83, 0
	global_load_dword v19, v156, s[82:83] nt
	s_add_u32 s82, s82, 0x1000
	s_addc_u32 s83, s83, 0
	global_load_dword v20, v156, s[82:83] nt
	s_add_u32 s82, s82, 0x1000
	s_addc_u32 s83, s83, 0
	global_load_dword v21, v156, s[82:83] nt
	s_add_u32 s82, s82, 0x1000
	s_addc_u32 s83, s83, 0
	global_load_dword v22, v156, s[82:83] nt
	s_add_u32 s82, s82, 0x1000
	s_addc_u32 s83, s83, 0
	global_load_dword v23, v156, s[82:83] nt
	s_add_u32 s82, s82, 0x1000
	s_addc_u32 s83, s83, 0
	global_load_dword v24, v156, s[82:83] nt
	s_add_u32 s82, s82, 0x1000
	s_addc_u32 s83, s83, 0
	global_load_dword v25, v156, s[82:83] nt
	s_add_u32 s82, s82, 0x1000
	s_addc_u32 s83, s83, 0
	global_load_dword v26, v156, s[82:83] nt
	s_add_u32 s82, s82, 0x1000
	s_addc_u32 s83, s83, 0
	global_load_dword v27, v156, s[82:83] nt
	s_add_u32 s82, s82, 0x1000
	s_addc_u32 s83, s83, 0
	global_load_dword v28, v156, s[82:83] nt
	s_add_u32 s82, s82, 0x1000
	s_addc_u32 s83, s83, 0
	global_load_dword v29, v156, s[82:83] nt
	s_add_u32 s82, s82, 0x1000
	s_addc_u32 s83, s83, 0
	global_load_dword v30, v156, s[82:83] nt
	s_add_u32 s82, s82, 0x1000
	s_addc_u32 s83, s83, 0
	global_load_dword v31, v156, s[82:83] nt
	s_add_u32 s82, s82, 0x1000
	s_addc_u32 s83, s83, 0
	global_load_dword v32, v156, s[82:83] nt
	s_add_u32 s82, s82, 0x1000
	s_addc_u32 s83, s83, 0
	global_load_dword v33, v156, s[82:83] nt
	s_add_u32 s82, s82, 0x1000
	s_addc_u32 s83, s83, 0
	global_load_dword v34, v156, s[82:83] nt
	s_add_u32 s82, s82, 0x1000
	s_addc_u32 s83, s83, 0
	global_load_dword v35, v156, s[82:83] nt
	s_add_u32 s82, s82, 0x1000
	s_addc_u32 s83, s83, 0
	global_load_dword v36, v156, s[82:83] nt
	s_add_u32 s82, s82, 0x1000
	s_addc_u32 s83, s83, 0
	global_load_dword v37, v156, s[82:83] nt
	s_add_u32 s82, s82, 0x1000
	s_addc_u32 s83, s83, 0
	global_load_dword v38, v156, s[82:83] nt
	s_add_u32 s82, s82, 0x1000
	s_addc_u32 s83, s83, 0
	global_load_dword v39, v156, s[82:83] nt
	s_add_u32 s82, s82, 0x1000
	s_addc_u32 s83, s83, 0
	global_load_dword v40, v156, s[82:83] nt
	s_add_u32 s82, s82, 0x1000
	s_addc_u32 s83, s83, 0
	global_load_dword v41, v156, s[82:83] nt
	s_add_u32 s82, s82, 0x1000
	s_addc_u32 s83, s83, 0
	global_load_dword v42, v156, s[82:83] nt
	s_add_u32 s82, s82, 0x1000
	s_addc_u32 s83, s83, 0
	global_load_dword v43, v156, s[82:83] nt
	s_add_u32 s82, s82, 0x1000
	s_addc_u32 s83, s83, 0
	global_load_dword v44, v156, s[82:83] nt
	s_add_u32 s82, s82, 0x1000
	s_addc_u32 s83, s83, 0
	global_load_dword v45, v156, s[82:83] nt
	s_add_u32 s82, s82, 0x1000
	s_addc_u32 s83, s83, 0
	global_load_dword v46, v156, s[82:83] nt
	s_add_u32 s82, s82, 0x1000
	s_addc_u32 s83, s83, 0
	global_load_dword v47, v156, s[82:83] nt
	s_add_u32 s82, s82, 0x1000
	s_addc_u32 s83, s83, 0
	global_load_dword v48, v156, s[82:83] nt
	s_add_u32 s82, s82, 0x1000
	s_addc_u32 s83, s83, 0
	global_load_dword v49, v156, s[82:83] nt
	s_add_u32 s82, s82, 0x1000
	s_addc_u32 s83, s83, 0
	global_load_dword v50, v156, s[82:83] nt
	s_add_u32 s82, s82, 0x1000
	s_addc_u32 s83, s83, 0
	global_load_dword v51, v156, s[82:83] nt
	s_add_u32 s82, s82, 0x1000
	s_addc_u32 s83, s83, 0
	global_load_dword v52, v156, s[82:83] nt
	s_add_u32 s82, s82, 0x1000
	s_addc_u32 s83, s83, 0
	global_load_dword v53, v156, s[82:83] nt
	s_add_u32 s82, s82, 0x1000
; __global__ void __launch_bounds__(NTHR, 2) hybrid_fwd(Args args) {
;     ...
;             for (int d = 0; d < 128; ++d) { const float wv = w_pool_out[(size_t)(gb + d) * 1024 + n] * pool_scale[gb + d];
; #pragma unroll
;                 for (int kk = 0; kk < 8; ++kk) a[kk] += pool_w[(size_t)(k0 + kk) * 128 + d] * wv; }
	s_addc_u32 s83, s83, 0
	global_load_dword v54, v156, s[82:83] nt
	s_add_u32 s82, s82, 0x1000
	s_addc_u32 s83, s83, 0
	global_load_dword v55, v156, s[82:83] nt
	s_add_u32 s82, s82, 0x1000
	s_addc_u32 s83, s83, 0
	global_load_dword v56, v156, s[82:83] nt
	s_add_u32 s82, s82, 0x1000
	s_addc_u32 s83, s83, 0
	global_load_dword v57, v156, s[82:83] nt
	s_add_u32 s82, s82, 0x1000
	s_addc_u32 s83, s83, 0
	global_load_dword v58, v156, s[82:83] nt
	s_add_u32 s82, s82, 0x1000
	s_addc_u32 s83, s83, 0
	global_load_dword v59, v156, s[82:83] nt
	s_add_u32 s82, s82, 0x1000
	s_addc_u32 s83, s83, 0
	global_load_dword v60, v156, s[82:83] nt
	s_add_u32 s82, s82, 0x1000
	s_addc_u32 s83, s83, 0
	global_load_dword v61, v156, s[82:83] nt
	s_add_u32 s82, s82, 0x1000
	s_addc_u32 s83, s83, 0
	global_load_dword v62, v156, s[82:83] nt
	s_add_u32 s82, s82, 0x1000
	s_addc_u32 s83, s83, 0
	global_load_dword v63, v156, s[82:83] nt
	s_add_u32 s82, s82, 0x1000
	s_addc_u32 s83, s83, 0
	global_load_dword v64, v156, s[82:83] nt
	s_add_u32 s82, s82, 0x1000
	s_addc_u32 s83, s83, 0
	global_load_dword v65, v156, s[82:83] nt
	s_add_u32 s82, s82, 0x1000
	s_addc_u32 s83, s83, 0
	global_load_dword v66, v156, s[82:83] nt
	s_add_u32 s82, s82, 0x1000
	s_addc_u32 s83, s83, 0
	global_load_dword v67, v156, s[82:83] nt
	s_add_u32 s82, s82, 0x1000
	s_addc_u32 s83, s83, 0
	global_load_dword v68, v156, s[82:83] nt
	s_add_u32 s82, s82, 0x1000
	s_addc_u32 s83, s83, 0
	global_load_dword v69, v156, s[82:83] nt
	s_add_u32 s82, s82, 0x1000
	s_addc_u32 s83, s83, 0
	global_load_dword v70, v156, s[82:83] nt
	s_add_u32 s82, s82, 0x1000
	s_addc_u32 s83, s83, 0
	global_load_dword v71, v156, s[82:83] nt
	s_add_u32 s82, s82, 0x1000
	s_addc_u32 s83, s83, 0
	global_load_dword v72, v156, s[82:83] nt
	s_add_u32 s82, s82, 0x1000
	s_addc_u32 s83, s83, 0
	global_load_dword v73, v156, s[82:83] nt
	s_add_u32 s82, s82, 0x1000
	s_addc_u32 s83, s83, 0
	global_load_dword v74, v156, s[82:83] nt
	s_add_u32 s82, s82, 0x1000
	s_addc_u32 s83, s83, 0
	global_load_dword v75, v156, s[82:83] nt
	s_add_u32 s82, s82, 0x1000
	s_addc_u32 s83, s83, 0
	global_load_dword v76, v156, s[82:83] nt
	s_add_u32 s82, s82, 0x1000
	s_addc_u32 s83, s83, 0
	global_load_dword v77, v156, s[82:83] nt
	s_add_u32 s82, s82, 0x1000
	s_addc_u32 s83, s83, 0
	global_load_dword v78, v156, s[82:83] nt
	s_add_u32 s82, s82, 0x1000
	s_addc_u32 s83, s83, 0
	global_load_dword v79, v156, s[82:83] nt
	s_add_u32 s82, s82, 0x1000
	s_addc_u32 s83, s83, 0
	global_load_dword v80, v156, s[82:83] nt
	s_add_u32 s82, s82, 0x1000
	s_addc_u32 s83, s83, 0
	global_load_dword v81, v156, s[82:83] nt
	s_add_u32 s82, s82, 0x1000
	s_addc_u32 s83, s83, 0
	global_load_dword v82, v156, s[82:83] nt
	s_add_u32 s82, s82, 0x1000
	s_addc_u32 s83, s83, 0
	global_load_dword v83, v156, s[82:83] nt
	s_add_u32 s82, s82, 0x1000
	s_addc_u32 s83, s83, 0
	global_load_dword v84, v156, s[82:83] nt
	s_add_u32 s82, s82, 0x1000
	s_addc_u32 s83, s83, 0
	global_load_dword v85, v156, s[82:83] nt
	s_add_u32 s82, s82, 0x1000
	s_addc_u32 s83, s83, 0
	global_load_dword v86, v156, s[82:83] nt
	s_add_u32 s82, s82, 0x1000
	s_addc_u32 s83, s83, 0
	global_load_dword v87, v156, s[82:83] nt
	s_add_u32 s82, s82, 0x1000
	s_addc_u32 s83, s83, 0
	global_load_dword v88, v156, s[82:83] nt
	s_add_u32 s82, s82, 0x1000
	s_addc_u32 s83, s83, 0
	global_load_dword v89, v156, s[82:83] nt
	s_add_u32 s82, s82, 0x1000
	s_addc_u32 s83, s83, 0
	global_load_dword v90, v156, s[82:83] nt
	s_add_u32 s82, s82, 0x1000
	s_addc_u32 s83, s83, 0
	global_load_dword v91, v156, s[82:83] nt
	s_add_u32 s82, s82, 0x1000
	s_addc_u32 s83, s83, 0
	global_load_dword v92, v156, s[82:83] nt
	s_add_u32 s82, s82, 0x1000
	s_addc_u32 s83, s83, 0
	global_load_dword v93, v156, s[82:83] nt
	s_add_u32 s82, s82, 0x1000
	s_addc_u32 s83, s83, 0
	global_load_dword v94, v156, s[82:83] nt
	s_add_u32 s82, s82, 0x1000
	s_addc_u32 s83, s83, 0
	global_load_dword v95, v156, s[82:83] nt
	s_add_u32 s82, s82, 0x1000
	s_addc_u32 s83, s83, 0
	global_load_dword v96, v156, s[82:83] nt
	s_add_u32 s82, s82, 0x1000
	s_addc_u32 s83, s83, 0
	global_load_dword v97, v156, s[82:83] nt
	s_add_u32 s82, s82, 0x1000
	s_addc_u32 s83, s83, 0
	global_load_dword v98, v156, s[82:83] nt
	s_add_u32 s82, s82, 0x1000
	s_addc_u32 s83, s83, 0
	global_load_dword v99, v156, s[82:83] nt
	s_add_u32 s82, s82, 0x1000
	s_addc_u32 s83, s83, 0
	global_load_dword v100, v156, s[82:83] nt
	s_add_u32 s82, s82, 0x1000
	s_addc_u32 s83, s83, 0
	global_load_dword v101, v156, s[82:83] nt
	s_add_u32 s82, s82, 0x1000
	s_addc_u32 s83, s83, 0
	global_load_dword v102, v156, s[82:83] nt
	s_add_u32 s82, s82, 0x1000
	s_addc_u32 s83, s83, 0
	global_load_dword v103, v156, s[82:83] nt
	s_add_u32 s82, s82, 0x1000
	s_addc_u32 s83, s83, 0
	global_load_dword v104, v156, s[82:83] nt
	s_add_u32 s82, s82, 0x1000
	s_addc_u32 s83, s83, 0
	global_load_dword v105, v156, s[82:83] nt
	s_add_u32 s82, s82, 0x1000
	s_addc_u32 s83, s83, 0
	global_load_dword v106, v156, s[82:83] nt
	s_add_u32 s82, s82, 0x1000
	s_addc_u32 s83, s83, 0
	global_load_dword v107, v156, s[82:83] nt
	s_add_u32 s82, s82, 0x1000
	s_addc_u32 s83, s83, 0
	global_load_dword v108, v156, s[82:83] nt
	s_add_u32 s82, s82, 0x1000
	s_addc_u32 s83, s83, 0
	global_load_dword v109, v156, s[82:83] nt
	s_add_u32 s82, s82, 0x1000
	s_addc_u32 s83, s83, 0
	global_load_dword v110, v156, s[82:83] nt
	s_add_u32 s82, s82, 0x1000
	s_addc_u32 s83, s83, 0
	global_load_dword v111, v156, s[82:83] nt
	s_add_u32 s82, s82, 0x1000
	s_addc_u32 s83, s83, 0
	global_load_dword v112, v156, s[82:83] nt
	s_add_u32 s82, s82, 0x1000
	s_addc_u32 s83, s83, 0
	global_load_dword v113, v156, s[82:83] nt
; __global__ void __launch_bounds__(NTHR, 2) hybrid_fwd(Args args) {
;     ...
;             float a[8];
; #pragma unroll
;             for (int kk = 0; kk < 8; ++kk) a[kk] = 0.f;
; #pragma unroll 8
;             for (int d = 0; d < 128; ++d) { const float wv = w_pool_out[(size_t)(gb + d) * 1024 + n] * pool_scale[gb + d];
; #pragma unroll
;                 for (int kk = 0; kk < 8; ++kk) a[kk] += pool_w[(size_t)(k0 + kk) * 128 + d] * wv; }
	s_add_u32 s82, s82, 0x1000
	s_addc_u32 s83, s83, 0
	global_load_dword v114, v156, s[82:83] nt
	s_add_u32 s82, s82, 0x1000
	s_addc_u32 s83, s83, 0
	global_load_dword v115, v156, s[82:83] nt
	s_add_u32 s82, s82, 0x1000
	s_addc_u32 s83, s83, 0
	global_load_dword v116, v156, s[82:83] nt
	s_add_u32 s82, s82, 0x1000
	s_addc_u32 s83, s83, 0
	global_load_dword v117, v156, s[82:83] nt
	s_add_u32 s82, s82, 0x1000
	s_addc_u32 s83, s83, 0
	global_load_dword v118, v156, s[82:83] nt
	s_add_u32 s82, s82, 0x1000
	s_addc_u32 s83, s83, 0
	global_load_dword v119, v156, s[82:83] nt
	s_add_u32 s82, s82, 0x1000
	s_addc_u32 s83, s83, 0
	global_load_dword v120, v156, s[82:83] nt
	s_add_u32 s82, s82, 0x1000
	s_addc_u32 s83, s83, 0
	global_load_dword v121, v156, s[82:83] nt
	s_add_u32 s82, s82, 0x1000
	s_addc_u32 s83, s83, 0
	global_load_dword v122, v156, s[82:83] nt
	s_add_u32 s82, s82, 0x1000
	s_addc_u32 s83, s83, 0
	global_load_dword v123, v156, s[82:83] nt
	s_add_u32 s82, s82, 0x1000
	s_addc_u32 s83, s83, 0
	global_load_dword v124, v156, s[82:83] nt
	s_add_u32 s82, s82, 0x1000
	s_addc_u32 s83, s83, 0
	global_load_dword v125, v156, s[82:83] nt
	s_add_u32 s82, s82, 0x1000
	s_addc_u32 s83, s83, 0
	global_load_dword v126, v156, s[82:83] nt
	s_add_u32 s82, s82, 0x1000
	s_addc_u32 s83, s83, 0
	global_load_dword v127, v156, s[82:83] nt
	s_lshl_b32 s79, s28, 2
	s_add_u32 s84, s10, s79
	s_addc_u32 s85, s11, 0
	global_load_dword v128, v157, s[84:85]
	global_load_dword v129, v157, s[84:85] offset:256
	s_lshl_b32 s79, s27, 9
	s_add_u32 s84, s8, s79
	s_addc_u32 s85, s9, 0
	global_load_dword v130, v157, s[84:85] offset:0
	global_load_dword v131, v157, s[84:85] offset:256
	global_load_dword v132, v157, s[84:85] offset:512
	global_load_dword v133, v157, s[84:85] offset:768
	global_load_dword v134, v157, s[84:85] offset:1024
	global_load_dword v135, v157, s[84:85] offset:1280
	global_load_dword v136, v157, s[84:85] offset:1536
	global_load_dword v137, v157, s[84:85] offset:1792
	global_load_dword v138, v157, s[84:85] offset:2048
	global_load_dword v139, v157, s[84:85] offset:2304
	global_load_dword v140, v157, s[84:85] offset:2560
	global_load_dword v141, v157, s[84:85] offset:2816
	global_load_dword v142, v157, s[84:85] offset:3072
	global_load_dword v143, v157, s[84:85] offset:3328
	global_load_dword v144, v157, s[84:85] offset:3584
	global_load_dword v145, v157, s[84:85] offset:3840
	v_mov_b32_e32 v146, 0
	v_mov_b32_e32 v147, 0
	v_mov_b32_e32 v148, 0
	v_mov_b32_e32 v149, 0
	v_mov_b32_e32 v150, 0
	v_mov_b32_e32 v151, 0
	v_mov_b32_e32 v152, 0
	v_mov_b32_e32 v153, 0
	s_waitcnt vmcnt(0)
	s_nop 0
	v_readlane_b32 s88, v128, 0
	v_readlane_b32 s77, v130, 0
	v_readlane_b32 s78, v132, 0
	v_readlane_b32 s79, v134, 0
	v_readlane_b32 s80, v136, 0
	v_readlane_b32 s81, v138, 0
	v_readlane_b32 s82, v140, 0
	v_readlane_b32 s83, v142, 0
	v_readlane_b32 s84, v144, 0
	v_mul_f32_e32 v154, s88, v0
	v_fmac_f32_e32 v146, s77, v154
	v_fmac_f32_e32 v147, s78, v154
	v_fmac_f32_e32 v148, s79, v154
	v_fmac_f32_e32 v149, s80, v154
	v_fmac_f32_e32 v150, s81, v154
	v_fmac_f32_e32 v151, s82, v154
	v_fmac_f32_e32 v152, s83, v154
	v_fmac_f32_e32 v153, s84, v154
	v_readlane_b32 s88, v128, 1
	v_readlane_b32 s77, v130, 1
	v_readlane_b32 s78, v132, 1
	v_readlane_b32 s79, v134, 1
	v_readlane_b32 s80, v136, 1
	v_readlane_b32 s81, v138, 1
	v_readlane_b32 s82, v140, 1
	v_readlane_b32 s83, v142, 1
	v_readlane_b32 s84, v144, 1
	v_mul_f32_e32 v154, s88, v1
	v_fmac_f32_e32 v146, s77, v154
	v_fmac_f32_e32 v147, s78, v154
	v_fmac_f32_e32 v148, s79, v154
	v_fmac_f32_e32 v149, s80, v154
	v_fmac_f32_e32 v150, s81, v154
	v_fmac_f32_e32 v151, s82, v154
	v_fmac_f32_e32 v152, s83, v154
	v_fmac_f32_e32 v153, s84, v154
	v_readlane_b32 s88, v128, 2
	v_readlane_b32 s77, v130, 2
	v_readlane_b32 s78, v132, 2
	v_readlane_b32 s79, v134, 2
	v_readlane_b32 s80, v136, 2
	v_readlane_b32 s81, v138, 2
	v_readlane_b32 s82, v140, 2
	v_readlane_b32 s83, v142, 2
	v_readlane_b32 s84, v144, 2
	v_mul_f32_e32 v154, s88, v2
	v_fmac_f32_e32 v146, s77, v154
	v_fmac_f32_e32 v147, s78, v154
	v_fmac_f32_e32 v148, s79, v154
	v_fmac_f32_e32 v149, s80, v154
	v_fmac_f32_e32 v150, s81, v154
	v_fmac_f32_e32 v151, s82, v154
	v_fmac_f32_e32 v152, s83, v154
	v_fmac_f32_e32 v153, s84, v154
	v_readlane_b32 s88, v128, 3
	v_readlane_b32 s77, v130, 3
	v_readlane_b32 s78, v132, 3
	v_readlane_b32 s79, v134, 3
	v_readlane_b32 s80, v136, 3
	v_readlane_b32 s81, v138, 3
	v_readlane_b32 s82, v140, 3
	v_readlane_b32 s83, v142, 3
	v_readlane_b32 s84, v144, 3
	v_mul_f32_e32 v154, s88, v3
	v_fmac_f32_e32 v146, s77, v154
	v_fmac_f32_e32 v147, s78, v154
	v_fmac_f32_e32 v148, s79, v154
	v_fmac_f32_e32 v149, s80, v154
	v_fmac_f32_e32 v150, s81, v154
	v_fmac_f32_e32 v151, s82, v154
	v_fmac_f32_e32 v152, s83, v154
	v_fmac_f32_e32 v153, s84, v154
	v_readlane_b32 s88, v128, 4
	v_readlane_b32 s77, v130, 4
	v_readlane_b32 s78, v132, 4
	v_readlane_b32 s79, v134, 4
	v_readlane_b32 s80, v136, 4
	v_readlane_b32 s81, v138, 4
	v_readlane_b32 s82, v140, 4
	v_readlane_b32 s83, v142, 4
	v_readlane_b32 s84, v144, 4
	v_mul_f32_e32 v154, s88, v4
	v_fmac_f32_e32 v146, s77, v154
	v_fmac_f32_e32 v147, s78, v154
	v_fmac_f32_e32 v148, s79, v154
	v_fmac_f32_e32 v149, s80, v154
	v_fmac_f32_e32 v150, s81, v154
	v_fmac_f32_e32 v151, s82, v154
	v_fmac_f32_e32 v152, s83, v154
	v_fmac_f32_e32 v153, s84, v154
	v_readlane_b32 s88, v128, 5
	v_readlane_b32 s77, v130, 5
	v_readlane_b32 s78, v132, 5
	v_readlane_b32 s79, v134, 5
	v_readlane_b32 s80, v136, 5
	v_readlane_b32 s81, v138, 5
	v_readlane_b32 s82, v140, 5
	v_readlane_b32 s83, v142, 5
	v_readlane_b32 s84, v144, 5
	v_mul_f32_e32 v154, s88, v5
; __global__ void __launch_bounds__(NTHR, 2) hybrid_fwd(Args args) {
;     ...
; #pragma unroll 8
;             for (int d = 0; d < 128; ++d) { const float wv = w_pool_out[(size_t)(gb + d) * 1024 + n] * pool_scale[gb + d];
; #pragma unroll
;                 for (int kk = 0; kk < 8; ++kk) a[kk] += pool_w[(size_t)(k0 + kk) * 128 + d] * wv; }
	v_fmac_f32_e32 v146, s77, v154
	v_fmac_f32_e32 v147, s78, v154
	v_fmac_f32_e32 v148, s79, v154
	v_fmac_f32_e32 v149, s80, v154
	v_fmac_f32_e32 v150, s81, v154
	v_fmac_f32_e32 v151, s82, v154
	v_fmac_f32_e32 v152, s83, v154
	v_fmac_f32_e32 v153, s84, v154
	v_readlane_b32 s88, v128, 6
	v_readlane_b32 s77, v130, 6
	v_readlane_b32 s78, v132, 6
	v_readlane_b32 s79, v134, 6
	v_readlane_b32 s80, v136, 6
	v_readlane_b32 s81, v138, 6
	v_readlane_b32 s82, v140, 6
	v_readlane_b32 s83, v142, 6
	v_readlane_b32 s84, v144, 6
	v_mul_f32_e32 v154, s88, v6
	v_fmac_f32_e32 v146, s77, v154
	v_fmac_f32_e32 v147, s78, v154
	v_fmac_f32_e32 v148, s79, v154
	v_fmac_f32_e32 v149, s80, v154
	v_fmac_f32_e32 v150, s81, v154
	v_fmac_f32_e32 v151, s82, v154
	v_fmac_f32_e32 v152, s83, v154
	v_fmac_f32_e32 v153, s84, v154
	v_readlane_b32 s88, v128, 7
	v_readlane_b32 s77, v130, 7
	v_readlane_b32 s78, v132, 7
	v_readlane_b32 s79, v134, 7
	v_readlane_b32 s80, v136, 7
	v_readlane_b32 s81, v138, 7
	v_readlane_b32 s82, v140, 7
	v_readlane_b32 s83, v142, 7
	v_readlane_b32 s84, v144, 7
	v_mul_f32_e32 v154, s88, v7
	v_fmac_f32_e32 v146, s77, v154
	v_fmac_f32_e32 v147, s78, v154
	v_fmac_f32_e32 v148, s79, v154
	v_fmac_f32_e32 v149, s80, v154
	v_fmac_f32_e32 v150, s81, v154
	v_fmac_f32_e32 v151, s82, v154
	v_fmac_f32_e32 v152, s83, v154
	v_fmac_f32_e32 v153, s84, v154
	v_readlane_b32 s88, v128, 8
	v_readlane_b32 s77, v130, 8
	v_readlane_b32 s78, v132, 8
	v_readlane_b32 s79, v134, 8
	v_readlane_b32 s80, v136, 8
	v_readlane_b32 s81, v138, 8
	v_readlane_b32 s82, v140, 8
	v_readlane_b32 s83, v142, 8
	v_readlane_b32 s84, v144, 8
	v_mul_f32_e32 v154, s88, v8
	v_fmac_f32_e32 v146, s77, v154
	v_fmac_f32_e32 v147, s78, v154
	v_fmac_f32_e32 v148, s79, v154
	v_fmac_f32_e32 v149, s80, v154
	v_fmac_f32_e32 v150, s81, v154
	v_fmac_f32_e32 v151, s82, v154
	v_fmac_f32_e32 v152, s83, v154
	v_fmac_f32_e32 v153, s84, v154
	v_readlane_b32 s88, v128, 9
	v_readlane_b32 s77, v130, 9
	v_readlane_b32 s78, v132, 9
	v_readlane_b32 s79, v134, 9
	v_readlane_b32 s80, v136, 9
	v_readlane_b32 s81, v138, 9
	v_readlane_b32 s82, v140, 9
	v_readlane_b32 s83, v142, 9
	v_readlane_b32 s84, v144, 9
	v_mul_f32_e32 v154, s88, v9
	v_fmac_f32_e32 v146, s77, v154
	v_fmac_f32_e32 v147, s78, v154
	v_fmac_f32_e32 v148, s79, v154
	v_fmac_f32_e32 v149, s80, v154
	v_fmac_f32_e32 v150, s81, v154
	v_fmac_f32_e32 v151, s82, v154
	v_fmac_f32_e32 v152, s83, v154
	v_fmac_f32_e32 v153, s84, v154
	v_readlane_b32 s88, v128, 10
	v_readlane_b32 s77, v130, 10
	v_readlane_b32 s78, v132, 10
	v_readlane_b32 s79, v134, 10
	v_readlane_b32 s80, v136, 10
	v_readlane_b32 s81, v138, 10
	v_readlane_b32 s82, v140, 10
	v_readlane_b32 s83, v142, 10
	v_readlane_b32 s84, v144, 10
	v_mul_f32_e32 v154, s88, v10
	v_fmac_f32_e32 v146, s77, v154
	v_fmac_f32_e32 v147, s78, v154
	v_fmac_f32_e32 v148, s79, v154
	v_fmac_f32_e32 v149, s80, v154
	v_fmac_f32_e32 v150, s81, v154
	v_fmac_f32_e32 v151, s82, v154
	v_fmac_f32_e32 v152, s83, v154
	v_fmac_f32_e32 v153, s84, v154
	v_readlane_b32 s88, v128, 11
	v_readlane_b32 s77, v130, 11
	v_readlane_b32 s78, v132, 11
	v_readlane_b32 s79, v134, 11
	v_readlane_b32 s80, v136, 11
	v_readlane_b32 s81, v138, 11
	v_readlane_b32 s82, v140, 11
	v_readlane_b32 s83, v142, 11
	v_readlane_b32 s84, v144, 11
	v_mul_f32_e32 v154, s88, v11
	v_fmac_f32_e32 v146, s77, v154
	v_fmac_f32_e32 v147, s78, v154
	v_fmac_f32_e32 v148, s79, v154
	v_fmac_f32_e32 v149, s80, v154
	v_fmac_f32_e32 v150, s81, v154
	v_fmac_f32_e32 v151, s82, v154
	v_fmac_f32_e32 v152, s83, v154
	v_fmac_f32_e32 v153, s84, v154
	v_readlane_b32 s88, v128, 12
	v_readlane_b32 s77, v130, 12
	v_readlane_b32 s78, v132, 12
	v_readlane_b32 s79, v134, 12
	v_readlane_b32 s80, v136, 12
	v_readlane_b32 s81, v138, 12
	v_readlane_b32 s82, v140, 12
	v_readlane_b32 s83, v142, 12
	v_readlane_b32 s84, v144, 12
	v_mul_f32_e32 v154, s88, v12
	v_fmac_f32_e32 v146, s77, v154
	v_fmac_f32_e32 v147, s78, v154
	v_fmac_f32_e32 v148, s79, v154
	v_fmac_f32_e32 v149, s80, v154
	v_fmac_f32_e32 v150, s81, v154
	v_fmac_f32_e32 v151, s82, v154
	v_fmac_f32_e32 v152, s83, v154
	v_fmac_f32_e32 v153, s84, v154
	v_readlane_b32 s88, v128, 13
	v_readlane_b32 s77, v130, 13
	v_readlane_b32 s78, v132, 13
	v_readlane_b32 s79, v134, 13
	v_readlane_b32 s80, v136, 13
	v_readlane_b32 s81, v138, 13
	v_readlane_b32 s82, v140, 13
	v_readlane_b32 s83, v142, 13
	v_readlane_b32 s84, v144, 13
	v_mul_f32_e32 v154, s88, v13
	v_fmac_f32_e32 v146, s77, v154
	v_fmac_f32_e32 v147, s78, v154
	v_fmac_f32_e32 v148, s79, v154
	v_fmac_f32_e32 v149, s80, v154
	v_fmac_f32_e32 v150, s81, v154
	v_fmac_f32_e32 v151, s82, v154
	v_fmac_f32_e32 v152, s83, v154
	v_fmac_f32_e32 v153, s84, v154
	v_readlane_b32 s88, v128, 14
	v_readlane_b32 s77, v130, 14
	v_readlane_b32 s78, v132, 14
	v_readlane_b32 s79, v134, 14
	v_readlane_b32 s80, v136, 14
	v_readlane_b32 s81, v138, 14
	v_readlane_b32 s82, v140, 14
	v_readlane_b32 s83, v142, 14
	v_readlane_b32 s84, v144, 14
	v_mul_f32_e32 v154, s88, v14
	v_fmac_f32_e32 v146, s77, v154
	v_fmac_f32_e32 v147, s78, v154
	v_fmac_f32_e32 v148, s79, v154
	v_fmac_f32_e32 v149, s80, v154
	v_fmac_f32_e32 v150, s81, v154
	v_fmac_f32_e32 v151, s82, v154
	v_fmac_f32_e32 v152, s83, v154
	v_fmac_f32_e32 v153, s84, v154
	v_readlane_b32 s88, v128, 15
	v_readlane_b32 s77, v130, 15
	v_readlane_b32 s78, v132, 15
	v_readlane_b32 s79, v134, 15
	v_readlane_b32 s80, v136, 15
	v_readlane_b32 s81, v138, 15
	v_readlane_b32 s82, v140, 15
	v_readlane_b32 s83, v142, 15
	v_readlane_b32 s84, v144, 15
	v_mul_f32_e32 v154, s88, v15
	v_fmac_f32_e32 v146, s77, v154
	v_fmac_f32_e32 v147, s78, v154
	v_fmac_f32_e32 v148, s79, v154
	v_fmac_f32_e32 v149, s80, v154
; __global__ void __launch_bounds__(NTHR, 2) hybrid_fwd(Args args) {
;     ...
; #pragma unroll 8
;             for (int d = 0; d < 128; ++d) { const float wv = w_pool_out[(size_t)(gb + d) * 1024 + n] * pool_scale[gb + d];
; #pragma unroll
;                 for (int kk = 0; kk < 8; ++kk) a[kk] += pool_w[(size_t)(k0 + kk) * 128 + d] * wv; }
	v_fmac_f32_e32 v150, s81, v154
	v_fmac_f32_e32 v151, s82, v154
	v_fmac_f32_e32 v152, s83, v154
	v_fmac_f32_e32 v153, s84, v154
	v_readlane_b32 s88, v128, 16
	v_readlane_b32 s77, v130, 16
	v_readlane_b32 s78, v132, 16
	v_readlane_b32 s79, v134, 16
	v_readlane_b32 s80, v136, 16
	v_readlane_b32 s81, v138, 16
	v_readlane_b32 s82, v140, 16
	v_readlane_b32 s83, v142, 16
	v_readlane_b32 s84, v144, 16
	v_mul_f32_e32 v154, s88, v16
	v_fmac_f32_e32 v146, s77, v154
	v_fmac_f32_e32 v147, s78, v154
	v_fmac_f32_e32 v148, s79, v154
	v_fmac_f32_e32 v149, s80, v154
	v_fmac_f32_e32 v150, s81, v154
	v_fmac_f32_e32 v151, s82, v154
	v_fmac_f32_e32 v152, s83, v154
	v_fmac_f32_e32 v153, s84, v154
	v_readlane_b32 s88, v128, 17
	v_readlane_b32 s77, v130, 17
	v_readlane_b32 s78, v132, 17
	v_readlane_b32 s79, v134, 17
	v_readlane_b32 s80, v136, 17
	v_readlane_b32 s81, v138, 17
	v_readlane_b32 s82, v140, 17
	v_readlane_b32 s83, v142, 17
	v_readlane_b32 s84, v144, 17
	v_mul_f32_e32 v154, s88, v17
	v_fmac_f32_e32 v146, s77, v154
	v_fmac_f32_e32 v147, s78, v154
	v_fmac_f32_e32 v148, s79, v154
	v_fmac_f32_e32 v149, s80, v154
	v_fmac_f32_e32 v150, s81, v154
	v_fmac_f32_e32 v151, s82, v154
	v_fmac_f32_e32 v152, s83, v154
	v_fmac_f32_e32 v153, s84, v154
	v_readlane_b32 s88, v128, 18
	v_readlane_b32 s77, v130, 18
	v_readlane_b32 s78, v132, 18
	v_readlane_b32 s79, v134, 18
	v_readlane_b32 s80, v136, 18
	v_readlane_b32 s81, v138, 18
	v_readlane_b32 s82, v140, 18
	v_readlane_b32 s83, v142, 18
	v_readlane_b32 s84, v144, 18
	v_mul_f32_e32 v154, s88, v18
	v_fmac_f32_e32 v146, s77, v154
	v_fmac_f32_e32 v147, s78, v154
	v_fmac_f32_e32 v148, s79, v154
	v_fmac_f32_e32 v149, s80, v154
	v_fmac_f32_e32 v150, s81, v154
	v_fmac_f32_e32 v151, s82, v154
	v_fmac_f32_e32 v152, s83, v154
	v_fmac_f32_e32 v153, s84, v154
	v_readlane_b32 s88, v128, 19
	v_readlane_b32 s77, v130, 19
	v_readlane_b32 s78, v132, 19
	v_readlane_b32 s79, v134, 19
	v_readlane_b32 s80, v136, 19
	v_readlane_b32 s81, v138, 19
	v_readlane_b32 s82, v140, 19
	v_readlane_b32 s83, v142, 19
	v_readlane_b32 s84, v144, 19
	v_mul_f32_e32 v154, s88, v19
	v_fmac_f32_e32 v146, s77, v154
	v_fmac_f32_e32 v147, s78, v154
	v_fmac_f32_e32 v148, s79, v154
	v_fmac_f32_e32 v149, s80, v154
	v_fmac_f32_e32 v150, s81, v154
	v_fmac_f32_e32 v151, s82, v154
	v_fmac_f32_e32 v152, s83, v154
	v_fmac_f32_e32 v153, s84, v154
	v_readlane_b32 s88, v128, 20
	v_readlane_b32 s77, v130, 20
	v_readlane_b32 s78, v132, 20
	v_readlane_b32 s79, v134, 20
	v_readlane_b32 s80, v136, 20
	v_readlane_b32 s81, v138, 20
	v_readlane_b32 s82, v140, 20
	v_readlane_b32 s83, v142, 20
	v_readlane_b32 s84, v144, 20
	v_mul_f32_e32 v154, s88, v20
	v_fmac_f32_e32 v146, s77, v154
	v_fmac_f32_e32 v147, s78, v154
	v_fmac_f32_e32 v148, s79, v154
	v_fmac_f32_e32 v149, s80, v154
	v_fmac_f32_e32 v150, s81, v154
	v_fmac_f32_e32 v151, s82, v154
	v_fmac_f32_e32 v152, s83, v154
	v_fmac_f32_e32 v153, s84, v154
	v_readlane_b32 s88, v128, 21
	v_readlane_b32 s77, v130, 21
	v_readlane_b32 s78, v132, 21
	v_readlane_b32 s79, v134, 21
	v_readlane_b32 s80, v136, 21
	v_readlane_b32 s81, v138, 21
	v_readlane_b32 s82, v140, 21
	v_readlane_b32 s83, v142, 21
	v_readlane_b32 s84, v144, 21
	v_mul_f32_e32 v154, s88, v21
	v_fmac_f32_e32 v146, s77, v154
	v_fmac_f32_e32 v147, s78, v154
	v_fmac_f32_e32 v148, s79, v154
	v_fmac_f32_e32 v149, s80, v154
	v_fmac_f32_e32 v150, s81, v154
	v_fmac_f32_e32 v151, s82, v154
	v_fmac_f32_e32 v152, s83, v154
	v_fmac_f32_e32 v153, s84, v154
	v_readlane_b32 s88, v128, 22
	v_readlane_b32 s77, v130, 22
	v_readlane_b32 s78, v132, 22
	v_readlane_b32 s79, v134, 22
	v_readlane_b32 s80, v136, 22
	v_readlane_b32 s81, v138, 22
	v_readlane_b32 s82, v140, 22
	v_readlane_b32 s83, v142, 22
	v_readlane_b32 s84, v144, 22
	v_mul_f32_e32 v154, s88, v22
	v_fmac_f32_e32 v146, s77, v154
	v_fmac_f32_e32 v147, s78, v154
	v_fmac_f32_e32 v148, s79, v154
	v_fmac_f32_e32 v149, s80, v154
	v_fmac_f32_e32 v150, s81, v154
	v_fmac_f32_e32 v151, s82, v154
	v_fmac_f32_e32 v152, s83, v154
	v_fmac_f32_e32 v153, s84, v154
	v_readlane_b32 s88, v128, 23
	v_readlane_b32 s77, v130, 23
	v_readlane_b32 s78, v132, 23
	v_readlane_b32 s79, v134, 23
	v_readlane_b32 s80, v136, 23
	v_readlane_b32 s81, v138, 23
	v_readlane_b32 s82, v140, 23
	v_readlane_b32 s83, v142, 23
	v_readlane_b32 s84, v144, 23
	v_mul_f32_e32 v154, s88, v23
	v_fmac_f32_e32 v146, s77, v154
	v_fmac_f32_e32 v147, s78, v154
	v_fmac_f32_e32 v148, s79, v154
	v_fmac_f32_e32 v149, s80, v154
	v_fmac_f32_e32 v150, s81, v154
	v_fmac_f32_e32 v151, s82, v154
	v_fmac_f32_e32 v152, s83, v154
	v_fmac_f32_e32 v153, s84, v154
	v_readlane_b32 s88, v128, 24
	v_readlane_b32 s77, v130, 24
	v_readlane_b32 s78, v132, 24
	v_readlane_b32 s79, v134, 24
	v_readlane_b32 s80, v136, 24
	v_readlane_b32 s81, v138, 24
	v_readlane_b32 s82, v140, 24
	v_readlane_b32 s83, v142, 24
	v_readlane_b32 s84, v144, 24
	v_mul_f32_e32 v154, s88, v24
	v_fmac_f32_e32 v146, s77, v154
	v_fmac_f32_e32 v147, s78, v154
	v_fmac_f32_e32 v148, s79, v154
	v_fmac_f32_e32 v149, s80, v154
	v_fmac_f32_e32 v150, s81, v154
	v_fmac_f32_e32 v151, s82, v154
	v_fmac_f32_e32 v152, s83, v154
	v_fmac_f32_e32 v153, s84, v154
	v_readlane_b32 s88, v128, 25
	v_readlane_b32 s77, v130, 25
	v_readlane_b32 s78, v132, 25
	v_readlane_b32 s79, v134, 25
	v_readlane_b32 s80, v136, 25
	v_readlane_b32 s81, v138, 25
	v_readlane_b32 s82, v140, 25
	v_readlane_b32 s83, v142, 25
	v_readlane_b32 s84, v144, 25
	v_mul_f32_e32 v154, s88, v25
	v_fmac_f32_e32 v146, s77, v154
	v_fmac_f32_e32 v147, s78, v154
	v_fmac_f32_e32 v148, s79, v154
	v_fmac_f32_e32 v149, s80, v154
	v_fmac_f32_e32 v150, s81, v154
	v_fmac_f32_e32 v151, s82, v154
; __global__ void __launch_bounds__(NTHR, 2) hybrid_fwd(Args args) {
;     ...
; #pragma unroll 8
;             for (int d = 0; d < 128; ++d) { const float wv = w_pool_out[(size_t)(gb + d) * 1024 + n] * pool_scale[gb + d];
; #pragma unroll
;                 for (int kk = 0; kk < 8; ++kk) a[kk] += pool_w[(size_t)(k0 + kk) * 128 + d] * wv; }
	v_fmac_f32_e32 v152, s83, v154
	v_fmac_f32_e32 v153, s84, v154
	v_readlane_b32 s88, v128, 26
	v_readlane_b32 s77, v130, 26
	v_readlane_b32 s78, v132, 26
	v_readlane_b32 s79, v134, 26
	v_readlane_b32 s80, v136, 26
	v_readlane_b32 s81, v138, 26
	v_readlane_b32 s82, v140, 26
	v_readlane_b32 s83, v142, 26
	v_readlane_b32 s84, v144, 26
	v_mul_f32_e32 v154, s88, v26
	v_fmac_f32_e32 v146, s77, v154
	v_fmac_f32_e32 v147, s78, v154
	v_fmac_f32_e32 v148, s79, v154
	v_fmac_f32_e32 v149, s80, v154
	v_fmac_f32_e32 v150, s81, v154
	v_fmac_f32_e32 v151, s82, v154
	v_fmac_f32_e32 v152, s83, v154
	v_fmac_f32_e32 v153, s84, v154
	v_readlane_b32 s88, v128, 27
	v_readlane_b32 s77, v130, 27
	v_readlane_b32 s78, v132, 27
	v_readlane_b32 s79, v134, 27
	v_readlane_b32 s80, v136, 27
	v_readlane_b32 s81, v138, 27
	v_readlane_b32 s82, v140, 27
	v_readlane_b32 s83, v142, 27
	v_readlane_b32 s84, v144, 27
	v_mul_f32_e32 v154, s88, v27
	v_fmac_f32_e32 v146, s77, v154
	v_fmac_f32_e32 v147, s78, v154
	v_fmac_f32_e32 v148, s79, v154
	v_fmac_f32_e32 v149, s80, v154
	v_fmac_f32_e32 v150, s81, v154
	v_fmac_f32_e32 v151, s82, v154
	v_fmac_f32_e32 v152, s83, v154
	v_fmac_f32_e32 v153, s84, v154
	v_readlane_b32 s88, v128, 28
	v_readlane_b32 s77, v130, 28
	v_readlane_b32 s78, v132, 28
	v_readlane_b32 s79, v134, 28
	v_readlane_b32 s80, v136, 28
	v_readlane_b32 s81, v138, 28
	v_readlane_b32 s82, v140, 28
	v_readlane_b32 s83, v142, 28
	v_readlane_b32 s84, v144, 28
	v_mul_f32_e32 v154, s88, v28
	v_fmac_f32_e32 v146, s77, v154
	v_fmac_f32_e32 v147, s78, v154
	v_fmac_f32_e32 v148, s79, v154
	v_fmac_f32_e32 v149, s80, v154
	v_fmac_f32_e32 v150, s81, v154
	v_fmac_f32_e32 v151, s82, v154
	v_fmac_f32_e32 v152, s83, v154
	v_fmac_f32_e32 v153, s84, v154
	v_readlane_b32 s88, v128, 29
	v_readlane_b32 s77, v130, 29
	v_readlane_b32 s78, v132, 29
	v_readlane_b32 s79, v134, 29
	v_readlane_b32 s80, v136, 29
	v_readlane_b32 s81, v138, 29
	v_readlane_b32 s82, v140, 29
	v_readlane_b32 s83, v142, 29
	v_readlane_b32 s84, v144, 29
	v_mul_f32_e32 v154, s88, v29
	v_fmac_f32_e32 v146, s77, v154
	v_fmac_f32_e32 v147, s78, v154
	v_fmac_f32_e32 v148, s79, v154
	v_fmac_f32_e32 v149, s80, v154
	v_fmac_f32_e32 v150, s81, v154
	v_fmac_f32_e32 v151, s82, v154
	v_fmac_f32_e32 v152, s83, v154
	v_fmac_f32_e32 v153, s84, v154
	v_readlane_b32 s88, v128, 30
	v_readlane_b32 s77, v130, 30
	v_readlane_b32 s78, v132, 30
	v_readlane_b32 s79, v134, 30
	v_readlane_b32 s80, v136, 30
	v_readlane_b32 s81, v138, 30
	v_readlane_b32 s82, v140, 30
	v_readlane_b32 s83, v142, 30
	v_readlane_b32 s84, v144, 30
	v_mul_f32_e32 v154, s88, v30
	v_fmac_f32_e32 v146, s77, v154
	v_fmac_f32_e32 v147, s78, v154
	v_fmac_f32_e32 v148, s79, v154
	v_fmac_f32_e32 v149, s80, v154
	v_fmac_f32_e32 v150, s81, v154
	v_fmac_f32_e32 v151, s82, v154
	v_fmac_f32_e32 v152, s83, v154
	v_fmac_f32_e32 v153, s84, v154
	v_readlane_b32 s88, v128, 31
	v_readlane_b32 s77, v130, 31
	v_readlane_b32 s78, v132, 31
	v_readlane_b32 s79, v134, 31
	v_readlane_b32 s80, v136, 31
	v_readlane_b32 s81, v138, 31
	v_readlane_b32 s82, v140, 31
	v_readlane_b32 s83, v142, 31
	v_readlane_b32 s84, v144, 31
	v_mul_f32_e32 v154, s88, v31
	v_fmac_f32_e32 v146, s77, v154
	v_fmac_f32_e32 v147, s78, v154
	v_fmac_f32_e32 v148, s79, v154
	v_fmac_f32_e32 v149, s80, v154
	v_fmac_f32_e32 v150, s81, v154
	v_fmac_f32_e32 v151, s82, v154
	v_fmac_f32_e32 v152, s83, v154
	v_fmac_f32_e32 v153, s84, v154
	v_readlane_b32 s88, v128, 32
	v_readlane_b32 s77, v130, 32
	v_readlane_b32 s78, v132, 32
	v_readlane_b32 s79, v134, 32
	v_readlane_b32 s80, v136, 32
	v_readlane_b32 s81, v138, 32
	v_readlane_b32 s82, v140, 32
	v_readlane_b32 s83, v142, 32
	v_readlane_b32 s84, v144, 32
	v_mul_f32_e32 v154, s88, v32
	v_fmac_f32_e32 v146, s77, v154
	v_fmac_f32_e32 v147, s78, v154
	v_fmac_f32_e32 v148, s79, v154
	v_fmac_f32_e32 v149, s80, v154
	v_fmac_f32_e32 v150, s81, v154
	v_fmac_f32_e32 v151, s82, v154
	v_fmac_f32_e32 v152, s83, v154
	v_fmac_f32_e32 v153, s84, v154
	v_readlane_b32 s88, v128, 33
	v_readlane_b32 s77, v130, 33
	v_readlane_b32 s78, v132, 33
	v_readlane_b32 s79, v134, 33
	v_readlane_b32 s80, v136, 33
	v_readlane_b32 s81, v138, 33
	v_readlane_b32 s82, v140, 33
	v_readlane_b32 s83, v142, 33
	v_readlane_b32 s84, v144, 33
	v_mul_f32_e32 v154, s88, v33
	v_fmac_f32_e32 v146, s77, v154
	v_fmac_f32_e32 v147, s78, v154
	v_fmac_f32_e32 v148, s79, v154
	v_fmac_f32_e32 v149, s80, v154
	v_fmac_f32_e32 v150, s81, v154
	v_fmac_f32_e32 v151, s82, v154
	v_fmac_f32_e32 v152, s83, v154
	v_fmac_f32_e32 v153, s84, v154
	v_readlane_b32 s88, v128, 34
	v_readlane_b32 s77, v130, 34
	v_readlane_b32 s78, v132, 34
	v_readlane_b32 s79, v134, 34
	v_readlane_b32 s80, v136, 34
	v_readlane_b32 s81, v138, 34
	v_readlane_b32 s82, v140, 34
	v_readlane_b32 s83, v142, 34
	v_readlane_b32 s84, v144, 34
	v_mul_f32_e32 v154, s88, v34
	v_fmac_f32_e32 v146, s77, v154
	v_fmac_f32_e32 v147, s78, v154
	v_fmac_f32_e32 v148, s79, v154
	v_fmac_f32_e32 v149, s80, v154
	v_fmac_f32_e32 v150, s81, v154
	v_fmac_f32_e32 v151, s82, v154
	v_fmac_f32_e32 v152, s83, v154
	v_fmac_f32_e32 v153, s84, v154
	v_readlane_b32 s88, v128, 35
	v_readlane_b32 s77, v130, 35
	v_readlane_b32 s78, v132, 35
	v_readlane_b32 s79, v134, 35
	v_readlane_b32 s80, v136, 35
	v_readlane_b32 s81, v138, 35
	v_readlane_b32 s82, v140, 35
	v_readlane_b32 s83, v142, 35
	v_readlane_b32 s84, v144, 35
	v_mul_f32_e32 v154, s88, v35
	v_fmac_f32_e32 v146, s77, v154
	v_fmac_f32_e32 v147, s78, v154
	v_fmac_f32_e32 v148, s79, v154
	v_fmac_f32_e32 v149, s80, v154
	v_fmac_f32_e32 v150, s81, v154
	v_fmac_f32_e32 v151, s82, v154
	v_fmac_f32_e32 v152, s83, v154
	v_fmac_f32_e32 v153, s84, v154
	v_readlane_b32 s88, v128, 36
; __global__ void __launch_bounds__(NTHR, 2) hybrid_fwd(Args args) {
;     ...
; #pragma unroll 8
;             for (int d = 0; d < 128; ++d) { const float wv = w_pool_out[(size_t)(gb + d) * 1024 + n] * pool_scale[gb + d];
; #pragma unroll
;                 for (int kk = 0; kk < 8; ++kk) a[kk] += pool_w[(size_t)(k0 + kk) * 128 + d] * wv; }
	v_readlane_b32 s77, v130, 36
	v_readlane_b32 s78, v132, 36
	v_readlane_b32 s79, v134, 36
	v_readlane_b32 s80, v136, 36
	v_readlane_b32 s81, v138, 36
	v_readlane_b32 s82, v140, 36
	v_readlane_b32 s83, v142, 36
	v_readlane_b32 s84, v144, 36
	v_mul_f32_e32 v154, s88, v36
	v_fmac_f32_e32 v146, s77, v154
	v_fmac_f32_e32 v147, s78, v154
	v_fmac_f32_e32 v148, s79, v154
	v_fmac_f32_e32 v149, s80, v154
	v_fmac_f32_e32 v150, s81, v154
	v_fmac_f32_e32 v151, s82, v154
	v_fmac_f32_e32 v152, s83, v154
	v_fmac_f32_e32 v153, s84, v154
	v_readlane_b32 s88, v128, 37
	v_readlane_b32 s77, v130, 37
	v_readlane_b32 s78, v132, 37
	v_readlane_b32 s79, v134, 37
	v_readlane_b32 s80, v136, 37
	v_readlane_b32 s81, v138, 37
	v_readlane_b32 s82, v140, 37
	v_readlane_b32 s83, v142, 37
	v_readlane_b32 s84, v144, 37
	v_mul_f32_e32 v154, s88, v37
	v_fmac_f32_e32 v146, s77, v154
	v_fmac_f32_e32 v147, s78, v154
	v_fmac_f32_e32 v148, s79, v154
	v_fmac_f32_e32 v149, s80, v154
	v_fmac_f32_e32 v150, s81, v154
	v_fmac_f32_e32 v151, s82, v154
	v_fmac_f32_e32 v152, s83, v154
	v_fmac_f32_e32 v153, s84, v154
	v_readlane_b32 s88, v128, 38
	v_readlane_b32 s77, v130, 38
	v_readlane_b32 s78, v132, 38
	v_readlane_b32 s79, v134, 38
	v_readlane_b32 s80, v136, 38
	v_readlane_b32 s81, v138, 38
	v_readlane_b32 s82, v140, 38
	v_readlane_b32 s83, v142, 38
	v_readlane_b32 s84, v144, 38
	v_mul_f32_e32 v154, s88, v38
	v_fmac_f32_e32 v146, s77, v154
	v_fmac_f32_e32 v147, s78, v154
	v_fmac_f32_e32 v148, s79, v154
	v_fmac_f32_e32 v149, s80, v154
	v_fmac_f32_e32 v150, s81, v154
	v_fmac_f32_e32 v151, s82, v154
	v_fmac_f32_e32 v152, s83, v154
	v_fmac_f32_e32 v153, s84, v154
	v_readlane_b32 s88, v128, 39
	v_readlane_b32 s77, v130, 39
	v_readlane_b32 s78, v132, 39
	v_readlane_b32 s79, v134, 39
	v_readlane_b32 s80, v136, 39
	v_readlane_b32 s81, v138, 39
	v_readlane_b32 s82, v140, 39
	v_readlane_b32 s83, v142, 39
	v_readlane_b32 s84, v144, 39
	v_mul_f32_e32 v154, s88, v39
	v_fmac_f32_e32 v146, s77, v154
	v_fmac_f32_e32 v147, s78, v154
	v_fmac_f32_e32 v148, s79, v154
	v_fmac_f32_e32 v149, s80, v154
	v_fmac_f32_e32 v150, s81, v154
	v_fmac_f32_e32 v151, s82, v154
	v_fmac_f32_e32 v152, s83, v154
	v_fmac_f32_e32 v153, s84, v154
	v_readlane_b32 s88, v128, 40
	v_readlane_b32 s77, v130, 40
	v_readlane_b32 s78, v132, 40
	v_readlane_b32 s79, v134, 40
	v_readlane_b32 s80, v136, 40
	v_readlane_b32 s81, v138, 40
	v_readlane_b32 s82, v140, 40
	v_readlane_b32 s83, v142, 40
	v_readlane_b32 s84, v144, 40
	v_mul_f32_e32 v154, s88, v40
	v_fmac_f32_e32 v146, s77, v154
	v_fmac_f32_e32 v147, s78, v154
	v_fmac_f32_e32 v148, s79, v154
	v_fmac_f32_e32 v149, s80, v154
	v_fmac_f32_e32 v150, s81, v154
	v_fmac_f32_e32 v151, s82, v154
	v_fmac_f32_e32 v152, s83, v154
	v_fmac_f32_e32 v153, s84, v154
	v_readlane_b32 s88, v128, 41
	v_readlane_b32 s77, v130, 41
	v_readlane_b32 s78, v132, 41
	v_readlane_b32 s79, v134, 41
	v_readlane_b32 s80, v136, 41
	v_readlane_b32 s81, v138, 41
	v_readlane_b32 s82, v140, 41
	v_readlane_b32 s83, v142, 41
	v_readlane_b32 s84, v144, 41
	v_mul_f32_e32 v154, s88, v41
	v_fmac_f32_e32 v146, s77, v154
	v_fmac_f32_e32 v147, s78, v154
	v_fmac_f32_e32 v148, s79, v154
	v_fmac_f32_e32 v149, s80, v154
	v_fmac_f32_e32 v150, s81, v154
	v_fmac_f32_e32 v151, s82, v154
	v_fmac_f32_e32 v152, s83, v154
	v_fmac_f32_e32 v153, s84, v154
	v_readlane_b32 s88, v128, 42
	v_readlane_b32 s77, v130, 42
	v_readlane_b32 s78, v132, 42
	v_readlane_b32 s79, v134, 42
	v_readlane_b32 s80, v136, 42
	v_readlane_b32 s81, v138, 42
	v_readlane_b32 s82, v140, 42
	v_readlane_b32 s83, v142, 42
	v_readlane_b32 s84, v144, 42
	v_mul_f32_e32 v154, s88, v42
	v_fmac_f32_e32 v146, s77, v154
	v_fmac_f32_e32 v147, s78, v154
	v_fmac_f32_e32 v148, s79, v154
	v_fmac_f32_e32 v149, s80, v154
	v_fmac_f32_e32 v150, s81, v154
	v_fmac_f32_e32 v151, s82, v154
	v_fmac_f32_e32 v152, s83, v154
	v_fmac_f32_e32 v153, s84, v154
	v_readlane_b32 s88, v128, 43
	v_readlane_b32 s77, v130, 43
	v_readlane_b32 s78, v132, 43
	v_readlane_b32 s79, v134, 43
	v_readlane_b32 s80, v136, 43
	v_readlane_b32 s81, v138, 43
	v_readlane_b32 s82, v140, 43
	v_readlane_b32 s83, v142, 43
	v_readlane_b32 s84, v144, 43
	v_mul_f32_e32 v154, s88, v43
	v_fmac_f32_e32 v146, s77, v154
	v_fmac_f32_e32 v147, s78, v154
	v_fmac_f32_e32 v148, s79, v154
	v_fmac_f32_e32 v149, s80, v154
	v_fmac_f32_e32 v150, s81, v154
	v_fmac_f32_e32 v151, s82, v154
	v_fmac_f32_e32 v152, s83, v154
	v_fmac_f32_e32 v153, s84, v154
	v_readlane_b32 s88, v128, 44
	v_readlane_b32 s77, v130, 44
	v_readlane_b32 s78, v132, 44
	v_readlane_b32 s79, v134, 44
	v_readlane_b32 s80, v136, 44
	v_readlane_b32 s81, v138, 44
	v_readlane_b32 s82, v140, 44
	v_readlane_b32 s83, v142, 44
	v_readlane_b32 s84, v144, 44
	v_mul_f32_e32 v154, s88, v44
	v_fmac_f32_e32 v146, s77, v154
	v_fmac_f32_e32 v147, s78, v154
	v_fmac_f32_e32 v148, s79, v154
	v_fmac_f32_e32 v149, s80, v154
	v_fmac_f32_e32 v150, s81, v154
	v_fmac_f32_e32 v151, s82, v154
	v_fmac_f32_e32 v152, s83, v154
	v_fmac_f32_e32 v153, s84, v154
	v_readlane_b32 s88, v128, 45
	v_readlane_b32 s77, v130, 45
	v_readlane_b32 s78, v132, 45
	v_readlane_b32 s79, v134, 45
	v_readlane_b32 s80, v136, 45
	v_readlane_b32 s81, v138, 45
	v_readlane_b32 s82, v140, 45
	v_readlane_b32 s83, v142, 45
	v_readlane_b32 s84, v144, 45
	v_mul_f32_e32 v154, s88, v45
	v_fmac_f32_e32 v146, s77, v154
	v_fmac_f32_e32 v147, s78, v154
	v_fmac_f32_e32 v148, s79, v154
	v_fmac_f32_e32 v149, s80, v154
	v_fmac_f32_e32 v150, s81, v154
	v_fmac_f32_e32 v151, s82, v154
	v_fmac_f32_e32 v152, s83, v154
	v_fmac_f32_e32 v153, s84, v154
	v_readlane_b32 s88, v128, 46
	v_readlane_b32 s77, v130, 46
	v_readlane_b32 s78, v132, 46
	v_readlane_b32 s79, v134, 46
; __global__ void __launch_bounds__(NTHR, 2) hybrid_fwd(Args args) {
;     ...
; #pragma unroll 8
;             for (int d = 0; d < 128; ++d) { const float wv = w_pool_out[(size_t)(gb + d) * 1024 + n] * pool_scale[gb + d];
; #pragma unroll
;                 for (int kk = 0; kk < 8; ++kk) a[kk] += pool_w[(size_t)(k0 + kk) * 128 + d] * wv; }
	v_readlane_b32 s80, v136, 46
	v_readlane_b32 s81, v138, 46
	v_readlane_b32 s82, v140, 46
	v_readlane_b32 s83, v142, 46
	v_readlane_b32 s84, v144, 46
	v_mul_f32_e32 v154, s88, v46
	v_fmac_f32_e32 v146, s77, v154
	v_fmac_f32_e32 v147, s78, v154
	v_fmac_f32_e32 v148, s79, v154
	v_fmac_f32_e32 v149, s80, v154
	v_fmac_f32_e32 v150, s81, v154
	v_fmac_f32_e32 v151, s82, v154
	v_fmac_f32_e32 v152, s83, v154
	v_fmac_f32_e32 v153, s84, v154
	v_readlane_b32 s88, v128, 47
	v_readlane_b32 s77, v130, 47
	v_readlane_b32 s78, v132, 47
	v_readlane_b32 s79, v134, 47
	v_readlane_b32 s80, v136, 47
	v_readlane_b32 s81, v138, 47
	v_readlane_b32 s82, v140, 47
	v_readlane_b32 s83, v142, 47
	v_readlane_b32 s84, v144, 47
	v_mul_f32_e32 v154, s88, v47
	v_fmac_f32_e32 v146, s77, v154
	v_fmac_f32_e32 v147, s78, v154
	v_fmac_f32_e32 v148, s79, v154
	v_fmac_f32_e32 v149, s80, v154
	v_fmac_f32_e32 v150, s81, v154
	v_fmac_f32_e32 v151, s82, v154
	v_fmac_f32_e32 v152, s83, v154
	v_fmac_f32_e32 v153, s84, v154
	v_readlane_b32 s88, v128, 48
	v_readlane_b32 s77, v130, 48
	v_readlane_b32 s78, v132, 48
	v_readlane_b32 s79, v134, 48
	v_readlane_b32 s80, v136, 48
	v_readlane_b32 s81, v138, 48
	v_readlane_b32 s82, v140, 48
	v_readlane_b32 s83, v142, 48
	v_readlane_b32 s84, v144, 48
	v_mul_f32_e32 v154, s88, v48
	v_fmac_f32_e32 v146, s77, v154
	v_fmac_f32_e32 v147, s78, v154
	v_fmac_f32_e32 v148, s79, v154
	v_fmac_f32_e32 v149, s80, v154
	v_fmac_f32_e32 v150, s81, v154
	v_fmac_f32_e32 v151, s82, v154
	v_fmac_f32_e32 v152, s83, v154
	v_fmac_f32_e32 v153, s84, v154
	v_readlane_b32 s88, v128, 49
	v_readlane_b32 s77, v130, 49
	v_readlane_b32 s78, v132, 49
	v_readlane_b32 s79, v134, 49
	v_readlane_b32 s80, v136, 49
	v_readlane_b32 s81, v138, 49
	v_readlane_b32 s82, v140, 49
	v_readlane_b32 s83, v142, 49
	v_readlane_b32 s84, v144, 49
	v_mul_f32_e32 v154, s88, v49
	v_fmac_f32_e32 v146, s77, v154
	v_fmac_f32_e32 v147, s78, v154
	v_fmac_f32_e32 v148, s79, v154
	v_fmac_f32_e32 v149, s80, v154
	v_fmac_f32_e32 v150, s81, v154
	v_fmac_f32_e32 v151, s82, v154
	v_fmac_f32_e32 v152, s83, v154
	v_fmac_f32_e32 v153, s84, v154
	v_readlane_b32 s88, v128, 50
	v_readlane_b32 s77, v130, 50
	v_readlane_b32 s78, v132, 50
	v_readlane_b32 s79, v134, 50
	v_readlane_b32 s80, v136, 50
	v_readlane_b32 s81, v138, 50
	v_readlane_b32 s82, v140, 50
	v_readlane_b32 s83, v142, 50
	v_readlane_b32 s84, v144, 50
	v_mul_f32_e32 v154, s88, v50
	v_fmac_f32_e32 v146, s77, v154
	v_fmac_f32_e32 v147, s78, v154
	v_fmac_f32_e32 v148, s79, v154
	v_fmac_f32_e32 v149, s80, v154
	v_fmac_f32_e32 v150, s81, v154
	v_fmac_f32_e32 v151, s82, v154
	v_fmac_f32_e32 v152, s83, v154
	v_fmac_f32_e32 v153, s84, v154
	v_readlane_b32 s88, v128, 51
	v_readlane_b32 s77, v130, 51
	v_readlane_b32 s78, v132, 51
	v_readlane_b32 s79, v134, 51
	v_readlane_b32 s80, v136, 51
	v_readlane_b32 s81, v138, 51
	v_readlane_b32 s82, v140, 51
	v_readlane_b32 s83, v142, 51
	v_readlane_b32 s84, v144, 51
	v_mul_f32_e32 v154, s88, v51
	v_fmac_f32_e32 v146, s77, v154
	v_fmac_f32_e32 v147, s78, v154
	v_fmac_f32_e32 v148, s79, v154
	v_fmac_f32_e32 v149, s80, v154
	v_fmac_f32_e32 v150, s81, v154
	v_fmac_f32_e32 v151, s82, v154
	v_fmac_f32_e32 v152, s83, v154
	v_fmac_f32_e32 v153, s84, v154
	v_readlane_b32 s88, v128, 52
	v_readlane_b32 s77, v130, 52
	v_readlane_b32 s78, v132, 52
	v_readlane_b32 s79, v134, 52
	v_readlane_b32 s80, v136, 52
	v_readlane_b32 s81, v138, 52
	v_readlane_b32 s82, v140, 52
	v_readlane_b32 s83, v142, 52
	v_readlane_b32 s84, v144, 52
	v_mul_f32_e32 v154, s88, v52
	v_fmac_f32_e32 v146, s77, v154
	v_fmac_f32_e32 v147, s78, v154
	v_fmac_f32_e32 v148, s79, v154
	v_fmac_f32_e32 v149, s80, v154
	v_fmac_f32_e32 v150, s81, v154
	v_fmac_f32_e32 v151, s82, v154
	v_fmac_f32_e32 v152, s83, v154
	v_fmac_f32_e32 v153, s84, v154
	v_readlane_b32 s88, v128, 53
	v_readlane_b32 s77, v130, 53
	v_readlane_b32 s78, v132, 53
	v_readlane_b32 s79, v134, 53
	v_readlane_b32 s80, v136, 53
	v_readlane_b32 s81, v138, 53
	v_readlane_b32 s82, v140, 53
	v_readlane_b32 s83, v142, 53
	v_readlane_b32 s84, v144, 53
	v_mul_f32_e32 v154, s88, v53
	v_fmac_f32_e32 v146, s77, v154
	v_fmac_f32_e32 v147, s78, v154
	v_fmac_f32_e32 v148, s79, v154
	v_fmac_f32_e32 v149, s80, v154
	v_fmac_f32_e32 v150, s81, v154
	v_fmac_f32_e32 v151, s82, v154
	v_fmac_f32_e32 v152, s83, v154
	v_fmac_f32_e32 v153, s84, v154
	v_readlane_b32 s88, v128, 54
	v_readlane_b32 s77, v130, 54
	v_readlane_b32 s78, v132, 54
	v_readlane_b32 s79, v134, 54
	v_readlane_b32 s80, v136, 54
	v_readlane_b32 s81, v138, 54
	v_readlane_b32 s82, v140, 54
	v_readlane_b32 s83, v142, 54
	v_readlane_b32 s84, v144, 54
	v_mul_f32_e32 v154, s88, v54
	v_fmac_f32_e32 v146, s77, v154
	v_fmac_f32_e32 v147, s78, v154
	v_fmac_f32_e32 v148, s79, v154
	v_fmac_f32_e32 v149, s80, v154
	v_fmac_f32_e32 v150, s81, v154
	v_fmac_f32_e32 v151, s82, v154
	v_fmac_f32_e32 v152, s83, v154
	v_fmac_f32_e32 v153, s84, v154
	v_readlane_b32 s88, v128, 55
	v_readlane_b32 s77, v130, 55
	v_readlane_b32 s78, v132, 55
	v_readlane_b32 s79, v134, 55
	v_readlane_b32 s80, v136, 55
	v_readlane_b32 s81, v138, 55
	v_readlane_b32 s82, v140, 55
	v_readlane_b32 s83, v142, 55
	v_readlane_b32 s84, v144, 55
	v_mul_f32_e32 v154, s88, v55
	v_fmac_f32_e32 v146, s77, v154
	v_fmac_f32_e32 v147, s78, v154
	v_fmac_f32_e32 v148, s79, v154
	v_fmac_f32_e32 v149, s80, v154
	v_fmac_f32_e32 v150, s81, v154
	v_fmac_f32_e32 v151, s82, v154
	v_fmac_f32_e32 v152, s83, v154
	v_fmac_f32_e32 v153, s84, v154
	v_readlane_b32 s88, v128, 56
	v_readlane_b32 s77, v130, 56
	v_readlane_b32 s78, v132, 56
	v_readlane_b32 s79, v134, 56
	v_readlane_b32 s80, v136, 56
	v_readlane_b32 s81, v138, 56
	v_readlane_b32 s82, v140, 56
; __global__ void __launch_bounds__(NTHR, 2) hybrid_fwd(Args args) {
;     ...
; #pragma unroll 8
;             for (int d = 0; d < 128; ++d) { const float wv = w_pool_out[(size_t)(gb + d) * 1024 + n] * pool_scale[gb + d];
; #pragma unroll
;                 for (int kk = 0; kk < 8; ++kk) a[kk] += pool_w[(size_t)(k0 + kk) * 128 + d] * wv; }
	v_readlane_b32 s83, v142, 56
	v_readlane_b32 s84, v144, 56
	v_mul_f32_e32 v154, s88, v56
	v_fmac_f32_e32 v146, s77, v154
	v_fmac_f32_e32 v147, s78, v154
	v_fmac_f32_e32 v148, s79, v154
	v_fmac_f32_e32 v149, s80, v154
	v_fmac_f32_e32 v150, s81, v154
	v_fmac_f32_e32 v151, s82, v154
	v_fmac_f32_e32 v152, s83, v154
	v_fmac_f32_e32 v153, s84, v154
	v_readlane_b32 s88, v128, 57
	v_readlane_b32 s77, v130, 57
	v_readlane_b32 s78, v132, 57
	v_readlane_b32 s79, v134, 57
	v_readlane_b32 s80, v136, 57
	v_readlane_b32 s81, v138, 57
	v_readlane_b32 s82, v140, 57
	v_readlane_b32 s83, v142, 57
	v_readlane_b32 s84, v144, 57
	v_mul_f32_e32 v154, s88, v57
	v_fmac_f32_e32 v146, s77, v154
	v_fmac_f32_e32 v147, s78, v154
	v_fmac_f32_e32 v148, s79, v154
	v_fmac_f32_e32 v149, s80, v154
	v_fmac_f32_e32 v150, s81, v154
	v_fmac_f32_e32 v151, s82, v154
	v_fmac_f32_e32 v152, s83, v154
	v_fmac_f32_e32 v153, s84, v154
	v_readlane_b32 s88, v128, 58
	v_readlane_b32 s77, v130, 58
	v_readlane_b32 s78, v132, 58
	v_readlane_b32 s79, v134, 58
	v_readlane_b32 s80, v136, 58
	v_readlane_b32 s81, v138, 58
	v_readlane_b32 s82, v140, 58
	v_readlane_b32 s83, v142, 58
	v_readlane_b32 s84, v144, 58
	v_mul_f32_e32 v154, s88, v58
	v_fmac_f32_e32 v146, s77, v154
	v_fmac_f32_e32 v147, s78, v154
	v_fmac_f32_e32 v148, s79, v154
	v_fmac_f32_e32 v149, s80, v154
	v_fmac_f32_e32 v150, s81, v154
	v_fmac_f32_e32 v151, s82, v154
	v_fmac_f32_e32 v152, s83, v154
	v_fmac_f32_e32 v153, s84, v154
	v_readlane_b32 s88, v128, 59
	v_readlane_b32 s77, v130, 59
	v_readlane_b32 s78, v132, 59
	v_readlane_b32 s79, v134, 59
	v_readlane_b32 s80, v136, 59
	v_readlane_b32 s81, v138, 59
	v_readlane_b32 s82, v140, 59
	v_readlane_b32 s83, v142, 59
	v_readlane_b32 s84, v144, 59
	v_mul_f32_e32 v154, s88, v59
	v_fmac_f32_e32 v146, s77, v154
	v_fmac_f32_e32 v147, s78, v154
	v_fmac_f32_e32 v148, s79, v154
	v_fmac_f32_e32 v149, s80, v154
	v_fmac_f32_e32 v150, s81, v154
	v_fmac_f32_e32 v151, s82, v154
	v_fmac_f32_e32 v152, s83, v154
	v_fmac_f32_e32 v153, s84, v154
	v_readlane_b32 s88, v128, 60
	v_readlane_b32 s77, v130, 60
	v_readlane_b32 s78, v132, 60
	v_readlane_b32 s79, v134, 60
	v_readlane_b32 s80, v136, 60
	v_readlane_b32 s81, v138, 60
	v_readlane_b32 s82, v140, 60
	v_readlane_b32 s83, v142, 60
	v_readlane_b32 s84, v144, 60
	v_mul_f32_e32 v154, s88, v60
	v_fmac_f32_e32 v146, s77, v154
	v_fmac_f32_e32 v147, s78, v154
	v_fmac_f32_e32 v148, s79, v154
	v_fmac_f32_e32 v149, s80, v154
	v_fmac_f32_e32 v150, s81, v154
	v_fmac_f32_e32 v151, s82, v154
	v_fmac_f32_e32 v152, s83, v154
	v_fmac_f32_e32 v153, s84, v154
	v_readlane_b32 s88, v128, 61
	v_readlane_b32 s77, v130, 61
	v_readlane_b32 s78, v132, 61
	v_readlane_b32 s79, v134, 61
	v_readlane_b32 s80, v136, 61
	v_readlane_b32 s81, v138, 61
	v_readlane_b32 s82, v140, 61
	v_readlane_b32 s83, v142, 61
	v_readlane_b32 s84, v144, 61
	v_mul_f32_e32 v154, s88, v61
	v_fmac_f32_e32 v146, s77, v154
	v_fmac_f32_e32 v147, s78, v154
	v_fmac_f32_e32 v148, s79, v154
	v_fmac_f32_e32 v149, s80, v154
	v_fmac_f32_e32 v150, s81, v154
	v_fmac_f32_e32 v151, s82, v154
	v_fmac_f32_e32 v152, s83, v154
	v_fmac_f32_e32 v153, s84, v154
	v_readlane_b32 s88, v128, 62
	v_readlane_b32 s77, v130, 62
	v_readlane_b32 s78, v132, 62
	v_readlane_b32 s79, v134, 62
	v_readlane_b32 s80, v136, 62
	v_readlane_b32 s81, v138, 62
	v_readlane_b32 s82, v140, 62
	v_readlane_b32 s83, v142, 62
	v_readlane_b32 s84, v144, 62
	v_mul_f32_e32 v154, s88, v62
	v_fmac_f32_e32 v146, s77, v154
	v_fmac_f32_e32 v147, s78, v154
	v_fmac_f32_e32 v148, s79, v154
	v_fmac_f32_e32 v149, s80, v154
	v_fmac_f32_e32 v150, s81, v154
	v_fmac_f32_e32 v151, s82, v154
	v_fmac_f32_e32 v152, s83, v154
	v_fmac_f32_e32 v153, s84, v154
	v_readlane_b32 s88, v128, 63
	v_readlane_b32 s77, v130, 63
	v_readlane_b32 s78, v132, 63
	v_readlane_b32 s79, v134, 63
	v_readlane_b32 s80, v136, 63
	v_readlane_b32 s81, v138, 63
	v_readlane_b32 s82, v140, 63
	v_readlane_b32 s83, v142, 63
	v_readlane_b32 s84, v144, 63
	v_mul_f32_e32 v154, s88, v63
	v_fmac_f32_e32 v146, s77, v154
	v_fmac_f32_e32 v147, s78, v154
	v_fmac_f32_e32 v148, s79, v154
	v_fmac_f32_e32 v149, s80, v154
	v_fmac_f32_e32 v150, s81, v154
	v_fmac_f32_e32 v151, s82, v154
	v_fmac_f32_e32 v152, s83, v154
	v_fmac_f32_e32 v153, s84, v154
	v_readlane_b32 s88, v129, 0
	v_readlane_b32 s77, v131, 0
	v_readlane_b32 s78, v133, 0
	v_readlane_b32 s79, v135, 0
	v_readlane_b32 s80, v137, 0
	v_readlane_b32 s81, v139, 0
	v_readlane_b32 s82, v141, 0
	v_readlane_b32 s83, v143, 0
	v_readlane_b32 s84, v145, 0
	v_mul_f32_e32 v154, s88, v64
	v_fmac_f32_e32 v146, s77, v154
	v_fmac_f32_e32 v147, s78, v154
	v_fmac_f32_e32 v148, s79, v154
	v_fmac_f32_e32 v149, s80, v154
	v_fmac_f32_e32 v150, s81, v154
	v_fmac_f32_e32 v151, s82, v154
	v_fmac_f32_e32 v152, s83, v154
	v_fmac_f32_e32 v153, s84, v154
	v_readlane_b32 s88, v129, 1
	v_readlane_b32 s77, v131, 1
	v_readlane_b32 s78, v133, 1
	v_readlane_b32 s79, v135, 1
	v_readlane_b32 s80, v137, 1
	v_readlane_b32 s81, v139, 1
	v_readlane_b32 s82, v141, 1
	v_readlane_b32 s83, v143, 1
	v_readlane_b32 s84, v145, 1
	v_mul_f32_e32 v154, s88, v65
	v_fmac_f32_e32 v146, s77, v154
	v_fmac_f32_e32 v147, s78, v154
	v_fmac_f32_e32 v148, s79, v154
	v_fmac_f32_e32 v149, s80, v154
	v_fmac_f32_e32 v150, s81, v154
	v_fmac_f32_e32 v151, s82, v154
	v_fmac_f32_e32 v152, s83, v154
	v_fmac_f32_e32 v153, s84, v154
	v_readlane_b32 s88, v129, 2
	v_readlane_b32 s77, v131, 2
	v_readlane_b32 s78, v133, 2
	v_readlane_b32 s79, v135, 2
	v_readlane_b32 s80, v137, 2
	v_readlane_b32 s81, v139, 2
	v_readlane_b32 s82, v141, 2
	v_readlane_b32 s83, v143, 2
	v_readlane_b32 s84, v145, 2
	v_mul_f32_e32 v154, s88, v66
	v_fmac_f32_e32 v146, s77, v154
; __global__ void __launch_bounds__(NTHR, 2) hybrid_fwd(Args args) {
;     ...
; #pragma unroll 8
;             for (int d = 0; d < 128; ++d) { const float wv = w_pool_out[(size_t)(gb + d) * 1024 + n] * pool_scale[gb + d];
; #pragma unroll
;                 for (int kk = 0; kk < 8; ++kk) a[kk] += pool_w[(size_t)(k0 + kk) * 128 + d] * wv; }
	v_fmac_f32_e32 v147, s78, v154
	v_fmac_f32_e32 v148, s79, v154
	v_fmac_f32_e32 v149, s80, v154
	v_fmac_f32_e32 v150, s81, v154
	v_fmac_f32_e32 v151, s82, v154
	v_fmac_f32_e32 v152, s83, v154
	v_fmac_f32_e32 v153, s84, v154
	v_readlane_b32 s88, v129, 3
	v_readlane_b32 s77, v131, 3
	v_readlane_b32 s78, v133, 3
	v_readlane_b32 s79, v135, 3
	v_readlane_b32 s80, v137, 3
	v_readlane_b32 s81, v139, 3
	v_readlane_b32 s82, v141, 3
	v_readlane_b32 s83, v143, 3
	v_readlane_b32 s84, v145, 3
	v_mul_f32_e32 v154, s88, v67
	v_fmac_f32_e32 v146, s77, v154
	v_fmac_f32_e32 v147, s78, v154
	v_fmac_f32_e32 v148, s79, v154
	v_fmac_f32_e32 v149, s80, v154
	v_fmac_f32_e32 v150, s81, v154
	v_fmac_f32_e32 v151, s82, v154
	v_fmac_f32_e32 v152, s83, v154
	v_fmac_f32_e32 v153, s84, v154
	v_readlane_b32 s88, v129, 4
	v_readlane_b32 s77, v131, 4
	v_readlane_b32 s78, v133, 4
	v_readlane_b32 s79, v135, 4
	v_readlane_b32 s80, v137, 4
	v_readlane_b32 s81, v139, 4
	v_readlane_b32 s82, v141, 4
	v_readlane_b32 s83, v143, 4
	v_readlane_b32 s84, v145, 4
	v_mul_f32_e32 v154, s88, v68
	v_fmac_f32_e32 v146, s77, v154
	v_fmac_f32_e32 v147, s78, v154
	v_fmac_f32_e32 v148, s79, v154
	v_fmac_f32_e32 v149, s80, v154
	v_fmac_f32_e32 v150, s81, v154
	v_fmac_f32_e32 v151, s82, v154
	v_fmac_f32_e32 v152, s83, v154
	v_fmac_f32_e32 v153, s84, v154
	v_readlane_b32 s88, v129, 5
	v_readlane_b32 s77, v131, 5
	v_readlane_b32 s78, v133, 5
	v_readlane_b32 s79, v135, 5
	v_readlane_b32 s80, v137, 5
	v_readlane_b32 s81, v139, 5
	v_readlane_b32 s82, v141, 5
	v_readlane_b32 s83, v143, 5
	v_readlane_b32 s84, v145, 5
	v_mul_f32_e32 v154, s88, v69
	v_fmac_f32_e32 v146, s77, v154
	v_fmac_f32_e32 v147, s78, v154
	v_fmac_f32_e32 v148, s79, v154
	v_fmac_f32_e32 v149, s80, v154
	v_fmac_f32_e32 v150, s81, v154
	v_fmac_f32_e32 v151, s82, v154
	v_fmac_f32_e32 v152, s83, v154
	v_fmac_f32_e32 v153, s84, v154
	v_readlane_b32 s88, v129, 6
	v_readlane_b32 s77, v131, 6
	v_readlane_b32 s78, v133, 6
	v_readlane_b32 s79, v135, 6
	v_readlane_b32 s80, v137, 6
	v_readlane_b32 s81, v139, 6
	v_readlane_b32 s82, v141, 6
	v_readlane_b32 s83, v143, 6
	v_readlane_b32 s84, v145, 6
	v_mul_f32_e32 v154, s88, v70
	v_fmac_f32_e32 v146, s77, v154
	v_fmac_f32_e32 v147, s78, v154
	v_fmac_f32_e32 v148, s79, v154
	v_fmac_f32_e32 v149, s80, v154
	v_fmac_f32_e32 v150, s81, v154
	v_fmac_f32_e32 v151, s82, v154
	v_fmac_f32_e32 v152, s83, v154
	v_fmac_f32_e32 v153, s84, v154
	v_readlane_b32 s88, v129, 7
	v_readlane_b32 s77, v131, 7
	v_readlane_b32 s78, v133, 7
	v_readlane_b32 s79, v135, 7
	v_readlane_b32 s80, v137, 7
	v_readlane_b32 s81, v139, 7
	v_readlane_b32 s82, v141, 7
	v_readlane_b32 s83, v143, 7
	v_readlane_b32 s84, v145, 7
	v_mul_f32_e32 v154, s88, v71
	v_fmac_f32_e32 v146, s77, v154
	v_fmac_f32_e32 v147, s78, v154
	v_fmac_f32_e32 v148, s79, v154
	v_fmac_f32_e32 v149, s80, v154
	v_fmac_f32_e32 v150, s81, v154
	v_fmac_f32_e32 v151, s82, v154
	v_fmac_f32_e32 v152, s83, v154
	v_fmac_f32_e32 v153, s84, v154
	v_readlane_b32 s88, v129, 8
	v_readlane_b32 s77, v131, 8
	v_readlane_b32 s78, v133, 8
	v_readlane_b32 s79, v135, 8
	v_readlane_b32 s80, v137, 8
	v_readlane_b32 s81, v139, 8
	v_readlane_b32 s82, v141, 8
	v_readlane_b32 s83, v143, 8
	v_readlane_b32 s84, v145, 8
	v_mul_f32_e32 v154, s88, v72
	v_fmac_f32_e32 v146, s77, v154
	v_fmac_f32_e32 v147, s78, v154
	v_fmac_f32_e32 v148, s79, v154
	v_fmac_f32_e32 v149, s80, v154
	v_fmac_f32_e32 v150, s81, v154
	v_fmac_f32_e32 v151, s82, v154
	v_fmac_f32_e32 v152, s83, v154
	v_fmac_f32_e32 v153, s84, v154
	v_readlane_b32 s88, v129, 9
	v_readlane_b32 s77, v131, 9
	v_readlane_b32 s78, v133, 9
	v_readlane_b32 s79, v135, 9
	v_readlane_b32 s80, v137, 9
	v_readlane_b32 s81, v139, 9
	v_readlane_b32 s82, v141, 9
	v_readlane_b32 s83, v143, 9
	v_readlane_b32 s84, v145, 9
	v_mul_f32_e32 v154, s88, v73
	v_fmac_f32_e32 v146, s77, v154
	v_fmac_f32_e32 v147, s78, v154
	v_fmac_f32_e32 v148, s79, v154
	v_fmac_f32_e32 v149, s80, v154
	v_fmac_f32_e32 v150, s81, v154
	v_fmac_f32_e32 v151, s82, v154
	v_fmac_f32_e32 v152, s83, v154
	v_fmac_f32_e32 v153, s84, v154
	v_readlane_b32 s88, v129, 10
	v_readlane_b32 s77, v131, 10
	v_readlane_b32 s78, v133, 10
	v_readlane_b32 s79, v135, 10
	v_readlane_b32 s80, v137, 10
	v_readlane_b32 s81, v139, 10
	v_readlane_b32 s82, v141, 10
	v_readlane_b32 s83, v143, 10
	v_readlane_b32 s84, v145, 10
	v_mul_f32_e32 v154, s88, v74
	v_fmac_f32_e32 v146, s77, v154
	v_fmac_f32_e32 v147, s78, v154
	v_fmac_f32_e32 v148, s79, v154
	v_fmac_f32_e32 v149, s80, v154
	v_fmac_f32_e32 v150, s81, v154
	v_fmac_f32_e32 v151, s82, v154
	v_fmac_f32_e32 v152, s83, v154
	v_fmac_f32_e32 v153, s84, v154
	v_readlane_b32 s88, v129, 11
	v_readlane_b32 s77, v131, 11
	v_readlane_b32 s78, v133, 11
	v_readlane_b32 s79, v135, 11
	v_readlane_b32 s80, v137, 11
	v_readlane_b32 s81, v139, 11
	v_readlane_b32 s82, v141, 11
	v_readlane_b32 s83, v143, 11
	v_readlane_b32 s84, v145, 11
	v_mul_f32_e32 v154, s88, v75
	v_fmac_f32_e32 v146, s77, v154
	v_fmac_f32_e32 v147, s78, v154
	v_fmac_f32_e32 v148, s79, v154
	v_fmac_f32_e32 v149, s80, v154
	v_fmac_f32_e32 v150, s81, v154
	v_fmac_f32_e32 v151, s82, v154
	v_fmac_f32_e32 v152, s83, v154
	v_fmac_f32_e32 v153, s84, v154
	v_readlane_b32 s88, v129, 12
	v_readlane_b32 s77, v131, 12
	v_readlane_b32 s78, v133, 12
	v_readlane_b32 s79, v135, 12
	v_readlane_b32 s80, v137, 12
	v_readlane_b32 s81, v139, 12
	v_readlane_b32 s82, v141, 12
	v_readlane_b32 s83, v143, 12
	v_readlane_b32 s84, v145, 12
	v_mul_f32_e32 v154, s88, v76
	v_fmac_f32_e32 v146, s77, v154
	v_fmac_f32_e32 v147, s78, v154
	v_fmac_f32_e32 v148, s79, v154
	v_fmac_f32_e32 v149, s80, v154
	v_fmac_f32_e32 v150, s81, v154
; __global__ void __launch_bounds__(NTHR, 2) hybrid_fwd(Args args) {
;     ...
; #pragma unroll 8
;             for (int d = 0; d < 128; ++d) { const float wv = w_pool_out[(size_t)(gb + d) * 1024 + n] * pool_scale[gb + d];
; #pragma unroll
;                 for (int kk = 0; kk < 8; ++kk) a[kk] += pool_w[(size_t)(k0 + kk) * 128 + d] * wv; }
	v_fmac_f32_e32 v151, s82, v154
	v_fmac_f32_e32 v152, s83, v154
	v_fmac_f32_e32 v153, s84, v154
	v_readlane_b32 s88, v129, 13
	v_readlane_b32 s77, v131, 13
	v_readlane_b32 s78, v133, 13
	v_readlane_b32 s79, v135, 13
	v_readlane_b32 s80, v137, 13
	v_readlane_b32 s81, v139, 13
	v_readlane_b32 s82, v141, 13
	v_readlane_b32 s83, v143, 13
	v_readlane_b32 s84, v145, 13
	v_mul_f32_e32 v154, s88, v77
	v_fmac_f32_e32 v146, s77, v154
	v_fmac_f32_e32 v147, s78, v154
	v_fmac_f32_e32 v148, s79, v154
	v_fmac_f32_e32 v149, s80, v154
	v_fmac_f32_e32 v150, s81, v154
	v_fmac_f32_e32 v151, s82, v154
	v_fmac_f32_e32 v152, s83, v154
	v_fmac_f32_e32 v153, s84, v154
	v_readlane_b32 s88, v129, 14
	v_readlane_b32 s77, v131, 14
	v_readlane_b32 s78, v133, 14
	v_readlane_b32 s79, v135, 14
	v_readlane_b32 s80, v137, 14
	v_readlane_b32 s81, v139, 14
	v_readlane_b32 s82, v141, 14
	v_readlane_b32 s83, v143, 14
	v_readlane_b32 s84, v145, 14
	v_mul_f32_e32 v154, s88, v78
	v_fmac_f32_e32 v146, s77, v154
	v_fmac_f32_e32 v147, s78, v154
	v_fmac_f32_e32 v148, s79, v154
	v_fmac_f32_e32 v149, s80, v154
	v_fmac_f32_e32 v150, s81, v154
	v_fmac_f32_e32 v151, s82, v154
	v_fmac_f32_e32 v152, s83, v154
	v_fmac_f32_e32 v153, s84, v154
	v_readlane_b32 s88, v129, 15
	v_readlane_b32 s77, v131, 15
	v_readlane_b32 s78, v133, 15
	v_readlane_b32 s79, v135, 15
	v_readlane_b32 s80, v137, 15
	v_readlane_b32 s81, v139, 15
	v_readlane_b32 s82, v141, 15
	v_readlane_b32 s83, v143, 15
	v_readlane_b32 s84, v145, 15
	v_mul_f32_e32 v154, s88, v79
	v_fmac_f32_e32 v146, s77, v154
	v_fmac_f32_e32 v147, s78, v154
	v_fmac_f32_e32 v148, s79, v154
	v_fmac_f32_e32 v149, s80, v154
	v_fmac_f32_e32 v150, s81, v154
	v_fmac_f32_e32 v151, s82, v154
	v_fmac_f32_e32 v152, s83, v154
	v_fmac_f32_e32 v153, s84, v154
	v_readlane_b32 s88, v129, 16
	v_readlane_b32 s77, v131, 16
	v_readlane_b32 s78, v133, 16
	v_readlane_b32 s79, v135, 16
	v_readlane_b32 s80, v137, 16
	v_readlane_b32 s81, v139, 16
	v_readlane_b32 s82, v141, 16
	v_readlane_b32 s83, v143, 16
	v_readlane_b32 s84, v145, 16
	v_mul_f32_e32 v154, s88, v80
	v_fmac_f32_e32 v146, s77, v154
	v_fmac_f32_e32 v147, s78, v154
	v_fmac_f32_e32 v148, s79, v154
	v_fmac_f32_e32 v149, s80, v154
	v_fmac_f32_e32 v150, s81, v154
	v_fmac_f32_e32 v151, s82, v154
	v_fmac_f32_e32 v152, s83, v154
	v_fmac_f32_e32 v153, s84, v154
	v_readlane_b32 s88, v129, 17
	v_readlane_b32 s77, v131, 17
	v_readlane_b32 s78, v133, 17
	v_readlane_b32 s79, v135, 17
	v_readlane_b32 s80, v137, 17
	v_readlane_b32 s81, v139, 17
	v_readlane_b32 s82, v141, 17
	v_readlane_b32 s83, v143, 17
	v_readlane_b32 s84, v145, 17
	v_mul_f32_e32 v154, s88, v81
	v_fmac_f32_e32 v146, s77, v154
	v_fmac_f32_e32 v147, s78, v154
	v_fmac_f32_e32 v148, s79, v154
	v_fmac_f32_e32 v149, s80, v154
	v_fmac_f32_e32 v150, s81, v154
	v_fmac_f32_e32 v151, s82, v154
	v_fmac_f32_e32 v152, s83, v154
	v_fmac_f32_e32 v153, s84, v154
	v_readlane_b32 s88, v129, 18
	v_readlane_b32 s77, v131, 18
	v_readlane_b32 s78, v133, 18
	v_readlane_b32 s79, v135, 18
	v_readlane_b32 s80, v137, 18
	v_readlane_b32 s81, v139, 18
	v_readlane_b32 s82, v141, 18
	v_readlane_b32 s83, v143, 18
	v_readlane_b32 s84, v145, 18
	v_mul_f32_e32 v154, s88, v82
	v_fmac_f32_e32 v146, s77, v154
	v_fmac_f32_e32 v147, s78, v154
	v_fmac_f32_e32 v148, s79, v154
	v_fmac_f32_e32 v149, s80, v154
	v_fmac_f32_e32 v150, s81, v154
	v_fmac_f32_e32 v151, s82, v154
	v_fmac_f32_e32 v152, s83, v154
	v_fmac_f32_e32 v153, s84, v154
	v_readlane_b32 s88, v129, 19
	v_readlane_b32 s77, v131, 19
	v_readlane_b32 s78, v133, 19
	v_readlane_b32 s79, v135, 19
	v_readlane_b32 s80, v137, 19
	v_readlane_b32 s81, v139, 19
	v_readlane_b32 s82, v141, 19
	v_readlane_b32 s83, v143, 19
	v_readlane_b32 s84, v145, 19
	v_mul_f32_e32 v154, s88, v83
	v_fmac_f32_e32 v146, s77, v154
	v_fmac_f32_e32 v147, s78, v154
	v_fmac_f32_e32 v148, s79, v154
	v_fmac_f32_e32 v149, s80, v154
	v_fmac_f32_e32 v150, s81, v154
	v_fmac_f32_e32 v151, s82, v154
	v_fmac_f32_e32 v152, s83, v154
	v_fmac_f32_e32 v153, s84, v154
	v_readlane_b32 s88, v129, 20
	v_readlane_b32 s77, v131, 20
	v_readlane_b32 s78, v133, 20
	v_readlane_b32 s79, v135, 20
	v_readlane_b32 s80, v137, 20
	v_readlane_b32 s81, v139, 20
	v_readlane_b32 s82, v141, 20
	v_readlane_b32 s83, v143, 20
	v_readlane_b32 s84, v145, 20
	v_mul_f32_e32 v154, s88, v84
	v_fmac_f32_e32 v146, s77, v154
	v_fmac_f32_e32 v147, s78, v154
	v_fmac_f32_e32 v148, s79, v154
	v_fmac_f32_e32 v149, s80, v154
	v_fmac_f32_e32 v150, s81, v154
	v_fmac_f32_e32 v151, s82, v154
	v_fmac_f32_e32 v152, s83, v154
	v_fmac_f32_e32 v153, s84, v154
	v_readlane_b32 s88, v129, 21
	v_readlane_b32 s77, v131, 21
	v_readlane_b32 s78, v133, 21
	v_readlane_b32 s79, v135, 21
	v_readlane_b32 s80, v137, 21
	v_readlane_b32 s81, v139, 21
	v_readlane_b32 s82, v141, 21
	v_readlane_b32 s83, v143, 21
	v_readlane_b32 s84, v145, 21
	v_mul_f32_e32 v154, s88, v85
	v_fmac_f32_e32 v146, s77, v154
	v_fmac_f32_e32 v147, s78, v154
	v_fmac_f32_e32 v148, s79, v154
	v_fmac_f32_e32 v149, s80, v154
	v_fmac_f32_e32 v150, s81, v154
	v_fmac_f32_e32 v151, s82, v154
	v_fmac_f32_e32 v152, s83, v154
	v_fmac_f32_e32 v153, s84, v154
	v_readlane_b32 s88, v129, 22
	v_readlane_b32 s77, v131, 22
	v_readlane_b32 s78, v133, 22
	v_readlane_b32 s79, v135, 22
	v_readlane_b32 s80, v137, 22
	v_readlane_b32 s81, v139, 22
	v_readlane_b32 s82, v141, 22
	v_readlane_b32 s83, v143, 22
	v_readlane_b32 s84, v145, 22
	v_mul_f32_e32 v154, s88, v86
	v_fmac_f32_e32 v146, s77, v154
	v_fmac_f32_e32 v147, s78, v154
	v_fmac_f32_e32 v148, s79, v154
	v_fmac_f32_e32 v149, s80, v154
	v_fmac_f32_e32 v150, s81, v154
	v_fmac_f32_e32 v151, s82, v154
	v_fmac_f32_e32 v152, s83, v154
; __global__ void __launch_bounds__(NTHR, 2) hybrid_fwd(Args args) {
;     ...
; #pragma unroll 8
;             for (int d = 0; d < 128; ++d) { const float wv = w_pool_out[(size_t)(gb + d) * 1024 + n] * pool_scale[gb + d];
; #pragma unroll
;                 for (int kk = 0; kk < 8; ++kk) a[kk] += pool_w[(size_t)(k0 + kk) * 128 + d] * wv; }
	v_fmac_f32_e32 v153, s84, v154
	v_readlane_b32 s88, v129, 23
	v_readlane_b32 s77, v131, 23
	v_readlane_b32 s78, v133, 23
	v_readlane_b32 s79, v135, 23
	v_readlane_b32 s80, v137, 23
	v_readlane_b32 s81, v139, 23
	v_readlane_b32 s82, v141, 23
	v_readlane_b32 s83, v143, 23
	v_readlane_b32 s84, v145, 23
	v_mul_f32_e32 v154, s88, v87
	v_fmac_f32_e32 v146, s77, v154
	v_fmac_f32_e32 v147, s78, v154
	v_fmac_f32_e32 v148, s79, v154
	v_fmac_f32_e32 v149, s80, v154
	v_fmac_f32_e32 v150, s81, v154
	v_fmac_f32_e32 v151, s82, v154
	v_fmac_f32_e32 v152, s83, v154
	v_fmac_f32_e32 v153, s84, v154
	v_readlane_b32 s88, v129, 24
	v_readlane_b32 s77, v131, 24
	v_readlane_b32 s78, v133, 24
	v_readlane_b32 s79, v135, 24
	v_readlane_b32 s80, v137, 24
	v_readlane_b32 s81, v139, 24
	v_readlane_b32 s82, v141, 24
	v_readlane_b32 s83, v143, 24
	v_readlane_b32 s84, v145, 24
	v_mul_f32_e32 v154, s88, v88
	v_fmac_f32_e32 v146, s77, v154
	v_fmac_f32_e32 v147, s78, v154
	v_fmac_f32_e32 v148, s79, v154
	v_fmac_f32_e32 v149, s80, v154
	v_fmac_f32_e32 v150, s81, v154
	v_fmac_f32_e32 v151, s82, v154
	v_fmac_f32_e32 v152, s83, v154
	v_fmac_f32_e32 v153, s84, v154
	v_readlane_b32 s88, v129, 25
	v_readlane_b32 s77, v131, 25
	v_readlane_b32 s78, v133, 25
	v_readlane_b32 s79, v135, 25
	v_readlane_b32 s80, v137, 25
	v_readlane_b32 s81, v139, 25
	v_readlane_b32 s82, v141, 25
	v_readlane_b32 s83, v143, 25
	v_readlane_b32 s84, v145, 25
	v_mul_f32_e32 v154, s88, v89
	v_fmac_f32_e32 v146, s77, v154
	v_fmac_f32_e32 v147, s78, v154
	v_fmac_f32_e32 v148, s79, v154
	v_fmac_f32_e32 v149, s80, v154
	v_fmac_f32_e32 v150, s81, v154
	v_fmac_f32_e32 v151, s82, v154
	v_fmac_f32_e32 v152, s83, v154
	v_fmac_f32_e32 v153, s84, v154
	v_readlane_b32 s88, v129, 26
	v_readlane_b32 s77, v131, 26
	v_readlane_b32 s78, v133, 26
	v_readlane_b32 s79, v135, 26
	v_readlane_b32 s80, v137, 26
	v_readlane_b32 s81, v139, 26
	v_readlane_b32 s82, v141, 26
	v_readlane_b32 s83, v143, 26
	v_readlane_b32 s84, v145, 26
	v_mul_f32_e32 v154, s88, v90
	v_fmac_f32_e32 v146, s77, v154
	v_fmac_f32_e32 v147, s78, v154
	v_fmac_f32_e32 v148, s79, v154
	v_fmac_f32_e32 v149, s80, v154
	v_fmac_f32_e32 v150, s81, v154
	v_fmac_f32_e32 v151, s82, v154
	v_fmac_f32_e32 v152, s83, v154
	v_fmac_f32_e32 v153, s84, v154
	v_readlane_b32 s88, v129, 27
	v_readlane_b32 s77, v131, 27
	v_readlane_b32 s78, v133, 27
	v_readlane_b32 s79, v135, 27
	v_readlane_b32 s80, v137, 27
	v_readlane_b32 s81, v139, 27
	v_readlane_b32 s82, v141, 27
	v_readlane_b32 s83, v143, 27
	v_readlane_b32 s84, v145, 27
	v_mul_f32_e32 v154, s88, v91
	v_fmac_f32_e32 v146, s77, v154
	v_fmac_f32_e32 v147, s78, v154
	v_fmac_f32_e32 v148, s79, v154
	v_fmac_f32_e32 v149, s80, v154
	v_fmac_f32_e32 v150, s81, v154
	v_fmac_f32_e32 v151, s82, v154
	v_fmac_f32_e32 v152, s83, v154
	v_fmac_f32_e32 v153, s84, v154
	v_readlane_b32 s88, v129, 28
	v_readlane_b32 s77, v131, 28
	v_readlane_b32 s78, v133, 28
	v_readlane_b32 s79, v135, 28
	v_readlane_b32 s80, v137, 28
	v_readlane_b32 s81, v139, 28
	v_readlane_b32 s82, v141, 28
	v_readlane_b32 s83, v143, 28
	v_readlane_b32 s84, v145, 28
	v_mul_f32_e32 v154, s88, v92
	v_fmac_f32_e32 v146, s77, v154
	v_fmac_f32_e32 v147, s78, v154
	v_fmac_f32_e32 v148, s79, v154
	v_fmac_f32_e32 v149, s80, v154
	v_fmac_f32_e32 v150, s81, v154
	v_fmac_f32_e32 v151, s82, v154
	v_fmac_f32_e32 v152, s83, v154
	v_fmac_f32_e32 v153, s84, v154
	v_readlane_b32 s88, v129, 29
	v_readlane_b32 s77, v131, 29
	v_readlane_b32 s78, v133, 29
	v_readlane_b32 s79, v135, 29
	v_readlane_b32 s80, v137, 29
	v_readlane_b32 s81, v139, 29
	v_readlane_b32 s82, v141, 29
	v_readlane_b32 s83, v143, 29
	v_readlane_b32 s84, v145, 29
	v_mul_f32_e32 v154, s88, v93
	v_fmac_f32_e32 v146, s77, v154
	v_fmac_f32_e32 v147, s78, v154
	v_fmac_f32_e32 v148, s79, v154
	v_fmac_f32_e32 v149, s80, v154
	v_fmac_f32_e32 v150, s81, v154
	v_fmac_f32_e32 v151, s82, v154
	v_fmac_f32_e32 v152, s83, v154
	v_fmac_f32_e32 v153, s84, v154
	v_readlane_b32 s88, v129, 30
	v_readlane_b32 s77, v131, 30
	v_readlane_b32 s78, v133, 30
	v_readlane_b32 s79, v135, 30
	v_readlane_b32 s80, v137, 30
	v_readlane_b32 s81, v139, 30
	v_readlane_b32 s82, v141, 30
	v_readlane_b32 s83, v143, 30
	v_readlane_b32 s84, v145, 30
	v_mul_f32_e32 v154, s88, v94
	v_fmac_f32_e32 v146, s77, v154
	v_fmac_f32_e32 v147, s78, v154
	v_fmac_f32_e32 v148, s79, v154
	v_fmac_f32_e32 v149, s80, v154
	v_fmac_f32_e32 v150, s81, v154
	v_fmac_f32_e32 v151, s82, v154
	v_fmac_f32_e32 v152, s83, v154
	v_fmac_f32_e32 v153, s84, v154
	v_readlane_b32 s88, v129, 31
	v_readlane_b32 s77, v131, 31
	v_readlane_b32 s78, v133, 31
	v_readlane_b32 s79, v135, 31
	v_readlane_b32 s80, v137, 31
	v_readlane_b32 s81, v139, 31
	v_readlane_b32 s82, v141, 31
	v_readlane_b32 s83, v143, 31
	v_readlane_b32 s84, v145, 31
	v_mul_f32_e32 v154, s88, v95
	v_fmac_f32_e32 v146, s77, v154
	v_fmac_f32_e32 v147, s78, v154
	v_fmac_f32_e32 v148, s79, v154
	v_fmac_f32_e32 v149, s80, v154
	v_fmac_f32_e32 v150, s81, v154
	v_fmac_f32_e32 v151, s82, v154
	v_fmac_f32_e32 v152, s83, v154
	v_fmac_f32_e32 v153, s84, v154
	v_readlane_b32 s88, v129, 32
	v_readlane_b32 s77, v131, 32
	v_readlane_b32 s78, v133, 32
	v_readlane_b32 s79, v135, 32
	v_readlane_b32 s80, v137, 32
	v_readlane_b32 s81, v139, 32
	v_readlane_b32 s82, v141, 32
	v_readlane_b32 s83, v143, 32
	v_readlane_b32 s84, v145, 32
	v_mul_f32_e32 v154, s88, v96
	v_fmac_f32_e32 v146, s77, v154
	v_fmac_f32_e32 v147, s78, v154
	v_fmac_f32_e32 v148, s79, v154
	v_fmac_f32_e32 v149, s80, v154
	v_fmac_f32_e32 v150, s81, v154
	v_fmac_f32_e32 v151, s82, v154
	v_fmac_f32_e32 v152, s83, v154
	v_fmac_f32_e32 v153, s84, v154
	v_readlane_b32 s88, v129, 33
	v_readlane_b32 s77, v131, 33
; __global__ void __launch_bounds__(NTHR, 2) hybrid_fwd(Args args) {
;     ...
; #pragma unroll 8
;             for (int d = 0; d < 128; ++d) { const float wv = w_pool_out[(size_t)(gb + d) * 1024 + n] * pool_scale[gb + d];
; #pragma unroll
;                 for (int kk = 0; kk < 8; ++kk) a[kk] += pool_w[(size_t)(k0 + kk) * 128 + d] * wv; }
	v_readlane_b32 s78, v133, 33
	v_readlane_b32 s79, v135, 33
	v_readlane_b32 s80, v137, 33
	v_readlane_b32 s81, v139, 33
	v_readlane_b32 s82, v141, 33
	v_readlane_b32 s83, v143, 33
	v_readlane_b32 s84, v145, 33
	v_mul_f32_e32 v154, s88, v97
	v_fmac_f32_e32 v146, s77, v154
	v_fmac_f32_e32 v147, s78, v154
	v_fmac_f32_e32 v148, s79, v154
	v_fmac_f32_e32 v149, s80, v154
	v_fmac_f32_e32 v150, s81, v154
	v_fmac_f32_e32 v151, s82, v154
	v_fmac_f32_e32 v152, s83, v154
	v_fmac_f32_e32 v153, s84, v154
	v_readlane_b32 s88, v129, 34
	v_readlane_b32 s77, v131, 34
	v_readlane_b32 s78, v133, 34
	v_readlane_b32 s79, v135, 34
	v_readlane_b32 s80, v137, 34
	v_readlane_b32 s81, v139, 34
	v_readlane_b32 s82, v141, 34
	v_readlane_b32 s83, v143, 34
	v_readlane_b32 s84, v145, 34
	v_mul_f32_e32 v154, s88, v98
	v_fmac_f32_e32 v146, s77, v154
	v_fmac_f32_e32 v147, s78, v154
	v_fmac_f32_e32 v148, s79, v154
	v_fmac_f32_e32 v149, s80, v154
	v_fmac_f32_e32 v150, s81, v154
	v_fmac_f32_e32 v151, s82, v154
	v_fmac_f32_e32 v152, s83, v154
	v_fmac_f32_e32 v153, s84, v154
	v_readlane_b32 s88, v129, 35
	v_readlane_b32 s77, v131, 35
	v_readlane_b32 s78, v133, 35
	v_readlane_b32 s79, v135, 35
	v_readlane_b32 s80, v137, 35
	v_readlane_b32 s81, v139, 35
	v_readlane_b32 s82, v141, 35
	v_readlane_b32 s83, v143, 35
	v_readlane_b32 s84, v145, 35
	v_mul_f32_e32 v154, s88, v99
	v_fmac_f32_e32 v146, s77, v154
	v_fmac_f32_e32 v147, s78, v154
	v_fmac_f32_e32 v148, s79, v154
	v_fmac_f32_e32 v149, s80, v154
	v_fmac_f32_e32 v150, s81, v154
	v_fmac_f32_e32 v151, s82, v154
	v_fmac_f32_e32 v152, s83, v154
	v_fmac_f32_e32 v153, s84, v154
	v_readlane_b32 s88, v129, 36
	v_readlane_b32 s77, v131, 36
	v_readlane_b32 s78, v133, 36
	v_readlane_b32 s79, v135, 36
	v_readlane_b32 s80, v137, 36
	v_readlane_b32 s81, v139, 36
	v_readlane_b32 s82, v141, 36
	v_readlane_b32 s83, v143, 36
	v_readlane_b32 s84, v145, 36
	v_mul_f32_e32 v154, s88, v100
	v_fmac_f32_e32 v146, s77, v154
	v_fmac_f32_e32 v147, s78, v154
	v_fmac_f32_e32 v148, s79, v154
	v_fmac_f32_e32 v149, s80, v154
	v_fmac_f32_e32 v150, s81, v154
	v_fmac_f32_e32 v151, s82, v154
	v_fmac_f32_e32 v152, s83, v154
	v_fmac_f32_e32 v153, s84, v154
	v_readlane_b32 s88, v129, 37
	v_readlane_b32 s77, v131, 37
	v_readlane_b32 s78, v133, 37
	v_readlane_b32 s79, v135, 37
	v_readlane_b32 s80, v137, 37
	v_readlane_b32 s81, v139, 37
	v_readlane_b32 s82, v141, 37
	v_readlane_b32 s83, v143, 37
	v_readlane_b32 s84, v145, 37
	v_mul_f32_e32 v154, s88, v101
	v_fmac_f32_e32 v146, s77, v154
	v_fmac_f32_e32 v147, s78, v154
	v_fmac_f32_e32 v148, s79, v154
	v_fmac_f32_e32 v149, s80, v154
	v_fmac_f32_e32 v150, s81, v154
	v_fmac_f32_e32 v151, s82, v154
	v_fmac_f32_e32 v152, s83, v154
	v_fmac_f32_e32 v153, s84, v154
	v_readlane_b32 s88, v129, 38
	v_readlane_b32 s77, v131, 38
	v_readlane_b32 s78, v133, 38
	v_readlane_b32 s79, v135, 38
	v_readlane_b32 s80, v137, 38
	v_readlane_b32 s81, v139, 38
	v_readlane_b32 s82, v141, 38
	v_readlane_b32 s83, v143, 38
	v_readlane_b32 s84, v145, 38
	v_mul_f32_e32 v154, s88, v102
	v_fmac_f32_e32 v146, s77, v154
	v_fmac_f32_e32 v147, s78, v154
	v_fmac_f32_e32 v148, s79, v154
	v_fmac_f32_e32 v149, s80, v154
	v_fmac_f32_e32 v150, s81, v154
	v_fmac_f32_e32 v151, s82, v154
	v_fmac_f32_e32 v152, s83, v154
	v_fmac_f32_e32 v153, s84, v154
	v_readlane_b32 s88, v129, 39
	v_readlane_b32 s77, v131, 39
	v_readlane_b32 s78, v133, 39
	v_readlane_b32 s79, v135, 39
	v_readlane_b32 s80, v137, 39
	v_readlane_b32 s81, v139, 39
	v_readlane_b32 s82, v141, 39
	v_readlane_b32 s83, v143, 39
	v_readlane_b32 s84, v145, 39
	v_mul_f32_e32 v154, s88, v103
	v_fmac_f32_e32 v146, s77, v154
	v_fmac_f32_e32 v147, s78, v154
	v_fmac_f32_e32 v148, s79, v154
	v_fmac_f32_e32 v149, s80, v154
	v_fmac_f32_e32 v150, s81, v154
	v_fmac_f32_e32 v151, s82, v154
	v_fmac_f32_e32 v152, s83, v154
	v_fmac_f32_e32 v153, s84, v154
	v_readlane_b32 s88, v129, 40
	v_readlane_b32 s77, v131, 40
	v_readlane_b32 s78, v133, 40
	v_readlane_b32 s79, v135, 40
	v_readlane_b32 s80, v137, 40
	v_readlane_b32 s81, v139, 40
	v_readlane_b32 s82, v141, 40
	v_readlane_b32 s83, v143, 40
	v_readlane_b32 s84, v145, 40
	v_mul_f32_e32 v154, s88, v104
	v_fmac_f32_e32 v146, s77, v154
	v_fmac_f32_e32 v147, s78, v154
	v_fmac_f32_e32 v148, s79, v154
	v_fmac_f32_e32 v149, s80, v154
	v_fmac_f32_e32 v150, s81, v154
	v_fmac_f32_e32 v151, s82, v154
	v_fmac_f32_e32 v152, s83, v154
	v_fmac_f32_e32 v153, s84, v154
	v_readlane_b32 s88, v129, 41
	v_readlane_b32 s77, v131, 41
	v_readlane_b32 s78, v133, 41
	v_readlane_b32 s79, v135, 41
	v_readlane_b32 s80, v137, 41
	v_readlane_b32 s81, v139, 41
	v_readlane_b32 s82, v141, 41
	v_readlane_b32 s83, v143, 41
	v_readlane_b32 s84, v145, 41
	v_mul_f32_e32 v154, s88, v105
	v_fmac_f32_e32 v146, s77, v154
	v_fmac_f32_e32 v147, s78, v154
	v_fmac_f32_e32 v148, s79, v154
	v_fmac_f32_e32 v149, s80, v154
	v_fmac_f32_e32 v150, s81, v154
	v_fmac_f32_e32 v151, s82, v154
	v_fmac_f32_e32 v152, s83, v154
	v_fmac_f32_e32 v153, s84, v154
	v_readlane_b32 s88, v129, 42
	v_readlane_b32 s77, v131, 42
	v_readlane_b32 s78, v133, 42
	v_readlane_b32 s79, v135, 42
	v_readlane_b32 s80, v137, 42
	v_readlane_b32 s81, v139, 42
	v_readlane_b32 s82, v141, 42
	v_readlane_b32 s83, v143, 42
	v_readlane_b32 s84, v145, 42
	v_mul_f32_e32 v154, s88, v106
	v_fmac_f32_e32 v146, s77, v154
	v_fmac_f32_e32 v147, s78, v154
	v_fmac_f32_e32 v148, s79, v154
	v_fmac_f32_e32 v149, s80, v154
	v_fmac_f32_e32 v150, s81, v154
	v_fmac_f32_e32 v151, s82, v154
	v_fmac_f32_e32 v152, s83, v154
	v_fmac_f32_e32 v153, s84, v154
	v_readlane_b32 s88, v129, 43
	v_readlane_b32 s77, v131, 43
	v_readlane_b32 s78, v133, 43
	v_readlane_b32 s79, v135, 43
; __global__ void __launch_bounds__(NTHR, 2) hybrid_fwd(Args args) {
;     ...
; #pragma unroll 8
;             for (int d = 0; d < 128; ++d) { const float wv = w_pool_out[(size_t)(gb + d) * 1024 + n] * pool_scale[gb + d];
; #pragma unroll
;                 for (int kk = 0; kk < 8; ++kk) a[kk] += pool_w[(size_t)(k0 + kk) * 128 + d] * wv; }
	v_readlane_b32 s80, v137, 43
	v_readlane_b32 s81, v139, 43
	v_readlane_b32 s82, v141, 43
	v_readlane_b32 s83, v143, 43
	v_readlane_b32 s84, v145, 43
	v_mul_f32_e32 v154, s88, v107
	v_fmac_f32_e32 v146, s77, v154
	v_fmac_f32_e32 v147, s78, v154
	v_fmac_f32_e32 v148, s79, v154
	v_fmac_f32_e32 v149, s80, v154
	v_fmac_f32_e32 v150, s81, v154
	v_fmac_f32_e32 v151, s82, v154
	v_fmac_f32_e32 v152, s83, v154
	v_fmac_f32_e32 v153, s84, v154
	v_readlane_b32 s88, v129, 44
	v_readlane_b32 s77, v131, 44
	v_readlane_b32 s78, v133, 44
	v_readlane_b32 s79, v135, 44
	v_readlane_b32 s80, v137, 44
	v_readlane_b32 s81, v139, 44
	v_readlane_b32 s82, v141, 44
	v_readlane_b32 s83, v143, 44
	v_readlane_b32 s84, v145, 44
	v_mul_f32_e32 v154, s88, v108
	v_fmac_f32_e32 v146, s77, v154
	v_fmac_f32_e32 v147, s78, v154
	v_fmac_f32_e32 v148, s79, v154
	v_fmac_f32_e32 v149, s80, v154
	v_fmac_f32_e32 v150, s81, v154
	v_fmac_f32_e32 v151, s82, v154
	v_fmac_f32_e32 v152, s83, v154
	v_fmac_f32_e32 v153, s84, v154
	v_readlane_b32 s88, v129, 45
	v_readlane_b32 s77, v131, 45
	v_readlane_b32 s78, v133, 45
	v_readlane_b32 s79, v135, 45
	v_readlane_b32 s80, v137, 45
	v_readlane_b32 s81, v139, 45
	v_readlane_b32 s82, v141, 45
	v_readlane_b32 s83, v143, 45
	v_readlane_b32 s84, v145, 45
	v_mul_f32_e32 v154, s88, v109
	v_fmac_f32_e32 v146, s77, v154
	v_fmac_f32_e32 v147, s78, v154
	v_fmac_f32_e32 v148, s79, v154
	v_fmac_f32_e32 v149, s80, v154
	v_fmac_f32_e32 v150, s81, v154
	v_fmac_f32_e32 v151, s82, v154
	v_fmac_f32_e32 v152, s83, v154
	v_fmac_f32_e32 v153, s84, v154
	v_readlane_b32 s88, v129, 46
	v_readlane_b32 s77, v131, 46
	v_readlane_b32 s78, v133, 46
	v_readlane_b32 s79, v135, 46
	v_readlane_b32 s80, v137, 46
	v_readlane_b32 s81, v139, 46
	v_readlane_b32 s82, v141, 46
	v_readlane_b32 s83, v143, 46
	v_readlane_b32 s84, v145, 46
	v_mul_f32_e32 v154, s88, v110
	v_fmac_f32_e32 v146, s77, v154
	v_fmac_f32_e32 v147, s78, v154
	v_fmac_f32_e32 v148, s79, v154
	v_fmac_f32_e32 v149, s80, v154
	v_fmac_f32_e32 v150, s81, v154
	v_fmac_f32_e32 v151, s82, v154
	v_fmac_f32_e32 v152, s83, v154
	v_fmac_f32_e32 v153, s84, v154
	v_readlane_b32 s88, v129, 47
	v_readlane_b32 s77, v131, 47
	v_readlane_b32 s78, v133, 47
	v_readlane_b32 s79, v135, 47
	v_readlane_b32 s80, v137, 47
	v_readlane_b32 s81, v139, 47
	v_readlane_b32 s82, v141, 47
	v_readlane_b32 s83, v143, 47
	v_readlane_b32 s84, v145, 47
	v_mul_f32_e32 v154, s88, v111
	v_fmac_f32_e32 v146, s77, v154
	v_fmac_f32_e32 v147, s78, v154
	v_fmac_f32_e32 v148, s79, v154
	v_fmac_f32_e32 v149, s80, v154
	v_fmac_f32_e32 v150, s81, v154
	v_fmac_f32_e32 v151, s82, v154
	v_fmac_f32_e32 v152, s83, v154
	v_fmac_f32_e32 v153, s84, v154
	v_readlane_b32 s88, v129, 48
	v_readlane_b32 s77, v131, 48
	v_readlane_b32 s78, v133, 48
	v_readlane_b32 s79, v135, 48
	v_readlane_b32 s80, v137, 48
	v_readlane_b32 s81, v139, 48
	v_readlane_b32 s82, v141, 48
	v_readlane_b32 s83, v143, 48
	v_readlane_b32 s84, v145, 48
	v_mul_f32_e32 v154, s88, v112
	v_fmac_f32_e32 v146, s77, v154
	v_fmac_f32_e32 v147, s78, v154
	v_fmac_f32_e32 v148, s79, v154
	v_fmac_f32_e32 v149, s80, v154
	v_fmac_f32_e32 v150, s81, v154
	v_fmac_f32_e32 v151, s82, v154
	v_fmac_f32_e32 v152, s83, v154
	v_fmac_f32_e32 v153, s84, v154
	v_readlane_b32 s88, v129, 49
	v_readlane_b32 s77, v131, 49
	v_readlane_b32 s78, v133, 49
	v_readlane_b32 s79, v135, 49
	v_readlane_b32 s80, v137, 49
	v_readlane_b32 s81, v139, 49
	v_readlane_b32 s82, v141, 49
	v_readlane_b32 s83, v143, 49
	v_readlane_b32 s84, v145, 49
	v_mul_f32_e32 v154, s88, v113
	v_fmac_f32_e32 v146, s77, v154
	v_fmac_f32_e32 v147, s78, v154
	v_fmac_f32_e32 v148, s79, v154
	v_fmac_f32_e32 v149, s80, v154
	v_fmac_f32_e32 v150, s81, v154
	v_fmac_f32_e32 v151, s82, v154
	v_fmac_f32_e32 v152, s83, v154
	v_fmac_f32_e32 v153, s84, v154
	v_readlane_b32 s88, v129, 50
	v_readlane_b32 s77, v131, 50
	v_readlane_b32 s78, v133, 50
	v_readlane_b32 s79, v135, 50
	v_readlane_b32 s80, v137, 50
	v_readlane_b32 s81, v139, 50
	v_readlane_b32 s82, v141, 50
	v_readlane_b32 s83, v143, 50
	v_readlane_b32 s84, v145, 50
	v_mul_f32_e32 v154, s88, v114
	v_fmac_f32_e32 v146, s77, v154
	v_fmac_f32_e32 v147, s78, v154
	v_fmac_f32_e32 v148, s79, v154
	v_fmac_f32_e32 v149, s80, v154
	v_fmac_f32_e32 v150, s81, v154
	v_fmac_f32_e32 v151, s82, v154
	v_fmac_f32_e32 v152, s83, v154
	v_fmac_f32_e32 v153, s84, v154
	v_readlane_b32 s88, v129, 51
	v_readlane_b32 s77, v131, 51
	v_readlane_b32 s78, v133, 51
	v_readlane_b32 s79, v135, 51
	v_readlane_b32 s80, v137, 51
	v_readlane_b32 s81, v139, 51
	v_readlane_b32 s82, v141, 51
	v_readlane_b32 s83, v143, 51
	v_readlane_b32 s84, v145, 51
	v_mul_f32_e32 v154, s88, v115
	v_fmac_f32_e32 v146, s77, v154
	v_fmac_f32_e32 v147, s78, v154
	v_fmac_f32_e32 v148, s79, v154
	v_fmac_f32_e32 v149, s80, v154
	v_fmac_f32_e32 v150, s81, v154
	v_fmac_f32_e32 v151, s82, v154
	v_fmac_f32_e32 v152, s83, v154
	v_fmac_f32_e32 v153, s84, v154
	v_readlane_b32 s88, v129, 52
	v_readlane_b32 s77, v131, 52
	v_readlane_b32 s78, v133, 52
	v_readlane_b32 s79, v135, 52
	v_readlane_b32 s80, v137, 52
	v_readlane_b32 s81, v139, 52
	v_readlane_b32 s82, v141, 52
	v_readlane_b32 s83, v143, 52
	v_readlane_b32 s84, v145, 52
	v_mul_f32_e32 v154, s88, v116
	v_fmac_f32_e32 v146, s77, v154
	v_fmac_f32_e32 v147, s78, v154
	v_fmac_f32_e32 v148, s79, v154
	v_fmac_f32_e32 v149, s80, v154
	v_fmac_f32_e32 v150, s81, v154
	v_fmac_f32_e32 v151, s82, v154
	v_fmac_f32_e32 v152, s83, v154
	v_fmac_f32_e32 v153, s84, v154
	v_readlane_b32 s88, v129, 53
	v_readlane_b32 s77, v131, 53
	v_readlane_b32 s78, v133, 53
	v_readlane_b32 s79, v135, 53
	v_readlane_b32 s80, v137, 53
	v_readlane_b32 s81, v139, 53
; __device__ __forceinline__ unsigned pk2(float lo, float hi) { return pg8::cvt_pk_bf16(lo, hi); }
; __global__ void __launch_bounds__(NTHR, 2) hybrid_fwd(Args args) {
;     ...
; #pragma unroll 8
;             for (int d = 0; d < 128; ++d) { const float wv = w_pool_out[(size_t)(gb + d) * 1024 + n] * pool_scale[gb + d];
; #pragma unroll
;                 for (int kk = 0; kk < 8; ++kk) a[kk] += pool_w[(size_t)(k0 + kk) * 128 + d] * wv; }
;             u32x4 o; o.x = pk2(a[0], a[1]); o.y = pk2(a[2], a[3]); o.z = pk2(a[4], a[5]); o.w = pk2(a[6], a[7]);
;             *(u32x4*)(Wmix + (size_t)n * 1024 + k0) = o; }
	v_readlane_b32 s82, v141, 53
	v_readlane_b32 s83, v143, 53
	v_readlane_b32 s84, v145, 53
	v_mul_f32_e32 v154, s88, v117
	v_fmac_f32_e32 v146, s77, v154
	v_fmac_f32_e32 v147, s78, v154
	v_fmac_f32_e32 v148, s79, v154
	v_fmac_f32_e32 v149, s80, v154
	v_fmac_f32_e32 v150, s81, v154
	v_fmac_f32_e32 v151, s82, v154
	v_fmac_f32_e32 v152, s83, v154
	v_fmac_f32_e32 v153, s84, v154
	v_readlane_b32 s88, v129, 54
	v_readlane_b32 s77, v131, 54
	v_readlane_b32 s78, v133, 54
	v_readlane_b32 s79, v135, 54
	v_readlane_b32 s80, v137, 54
	v_readlane_b32 s81, v139, 54
	v_readlane_b32 s82, v141, 54
	v_readlane_b32 s83, v143, 54
	v_readlane_b32 s84, v145, 54
	v_mul_f32_e32 v154, s88, v118
	v_fmac_f32_e32 v146, s77, v154
	v_fmac_f32_e32 v147, s78, v154
	v_fmac_f32_e32 v148, s79, v154
	v_fmac_f32_e32 v149, s80, v154
	v_fmac_f32_e32 v150, s81, v154
	v_fmac_f32_e32 v151, s82, v154
	v_fmac_f32_e32 v152, s83, v154
	v_fmac_f32_e32 v153, s84, v154
	v_readlane_b32 s88, v129, 55
	v_readlane_b32 s77, v131, 55
	v_readlane_b32 s78, v133, 55
	v_readlane_b32 s79, v135, 55
	v_readlane_b32 s80, v137, 55
	v_readlane_b32 s81, v139, 55
	v_readlane_b32 s82, v141, 55
	v_readlane_b32 s83, v143, 55
	v_readlane_b32 s84, v145, 55
	v_mul_f32_e32 v154, s88, v119
	v_fmac_f32_e32 v146, s77, v154
	v_fmac_f32_e32 v147, s78, v154
	v_fmac_f32_e32 v148, s79, v154
	v_fmac_f32_e32 v149, s80, v154
	v_fmac_f32_e32 v150, s81, v154
	v_fmac_f32_e32 v151, s82, v154
	v_fmac_f32_e32 v152, s83, v154
	v_fmac_f32_e32 v153, s84, v154
	v_readlane_b32 s88, v129, 56
	v_readlane_b32 s77, v131, 56
	v_readlane_b32 s78, v133, 56
	v_readlane_b32 s79, v135, 56
	v_readlane_b32 s80, v137, 56
	v_readlane_b32 s81, v139, 56
	v_readlane_b32 s82, v141, 56
	v_readlane_b32 s83, v143, 56
	v_readlane_b32 s84, v145, 56
	v_mul_f32_e32 v154, s88, v120
	v_fmac_f32_e32 v146, s77, v154
	v_fmac_f32_e32 v147, s78, v154
	v_fmac_f32_e32 v148, s79, v154
	v_fmac_f32_e32 v149, s80, v154
	v_fmac_f32_e32 v150, s81, v154
	v_fmac_f32_e32 v151, s82, v154
	v_fmac_f32_e32 v152, s83, v154
	v_fmac_f32_e32 v153, s84, v154
	v_readlane_b32 s88, v129, 57
	v_readlane_b32 s77, v131, 57
	v_readlane_b32 s78, v133, 57
	v_readlane_b32 s79, v135, 57
	v_readlane_b32 s80, v137, 57
	v_readlane_b32 s81, v139, 57
	v_readlane_b32 s82, v141, 57
	v_readlane_b32 s83, v143, 57
	v_readlane_b32 s84, v145, 57
	v_mul_f32_e32 v154, s88, v121
	v_fmac_f32_e32 v146, s77, v154
	v_fmac_f32_e32 v147, s78, v154
	v_fmac_f32_e32 v148, s79, v154
	v_fmac_f32_e32 v149, s80, v154
	v_fmac_f32_e32 v150, s81, v154
	v_fmac_f32_e32 v151, s82, v154
	v_fmac_f32_e32 v152, s83, v154
	v_fmac_f32_e32 v153, s84, v154
	v_readlane_b32 s88, v129, 58
	v_readlane_b32 s77, v131, 58
	v_readlane_b32 s78, v133, 58
	v_readlane_b32 s79, v135, 58
	v_readlane_b32 s80, v137, 58
	v_readlane_b32 s81, v139, 58
	v_readlane_b32 s82, v141, 58
	v_readlane_b32 s83, v143, 58
	v_readlane_b32 s84, v145, 58
	v_mul_f32_e32 v154, s88, v122
	v_fmac_f32_e32 v146, s77, v154
	v_fmac_f32_e32 v147, s78, v154
	v_fmac_f32_e32 v148, s79, v154
	v_fmac_f32_e32 v149, s80, v154
	v_fmac_f32_e32 v150, s81, v154
	v_fmac_f32_e32 v151, s82, v154
	v_fmac_f32_e32 v152, s83, v154
	v_fmac_f32_e32 v153, s84, v154
	v_readlane_b32 s88, v129, 59
	v_readlane_b32 s77, v131, 59
	v_readlane_b32 s78, v133, 59
	v_readlane_b32 s79, v135, 59
	v_readlane_b32 s80, v137, 59
	v_readlane_b32 s81, v139, 59
	v_readlane_b32 s82, v141, 59
	v_readlane_b32 s83, v143, 59
	v_readlane_b32 s84, v145, 59
	v_mul_f32_e32 v154, s88, v123
	v_fmac_f32_e32 v146, s77, v154
	v_fmac_f32_e32 v147, s78, v154
	v_fmac_f32_e32 v148, s79, v154
	v_fmac_f32_e32 v149, s80, v154
	v_fmac_f32_e32 v150, s81, v154
	v_fmac_f32_e32 v151, s82, v154
	v_fmac_f32_e32 v152, s83, v154
	v_fmac_f32_e32 v153, s84, v154
	v_readlane_b32 s88, v129, 60
	v_readlane_b32 s77, v131, 60
	v_readlane_b32 s78, v133, 60
	v_readlane_b32 s79, v135, 60
	v_readlane_b32 s80, v137, 60
	v_readlane_b32 s81, v139, 60
	v_readlane_b32 s82, v141, 60
	v_readlane_b32 s83, v143, 60
	v_readlane_b32 s84, v145, 60
	v_mul_f32_e32 v154, s88, v124
	v_fmac_f32_e32 v146, s77, v154
	v_fmac_f32_e32 v147, s78, v154
	v_fmac_f32_e32 v148, s79, v154
	v_fmac_f32_e32 v149, s80, v154
	v_fmac_f32_e32 v150, s81, v154
	v_fmac_f32_e32 v151, s82, v154
	v_fmac_f32_e32 v152, s83, v154
	v_fmac_f32_e32 v153, s84, v154
	v_readlane_b32 s88, v129, 61
	v_readlane_b32 s77, v131, 61
	v_readlane_b32 s78, v133, 61
	v_readlane_b32 s79, v135, 61
	v_readlane_b32 s80, v137, 61
	v_readlane_b32 s81, v139, 61
	v_readlane_b32 s82, v141, 61
	v_readlane_b32 s83, v143, 61
	v_readlane_b32 s84, v145, 61
	v_mul_f32_e32 v154, s88, v125
	v_fmac_f32_e32 v146, s77, v154
	v_fmac_f32_e32 v147, s78, v154
	v_fmac_f32_e32 v148, s79, v154
	v_fmac_f32_e32 v149, s80, v154
	v_fmac_f32_e32 v150, s81, v154
	v_fmac_f32_e32 v151, s82, v154
	v_fmac_f32_e32 v152, s83, v154
	v_fmac_f32_e32 v153, s84, v154
	v_readlane_b32 s88, v129, 62
	v_readlane_b32 s77, v131, 62
	v_readlane_b32 s78, v133, 62
	v_readlane_b32 s79, v135, 62
	v_readlane_b32 s80, v137, 62
	v_readlane_b32 s81, v139, 62
	v_readlane_b32 s82, v141, 62
	v_readlane_b32 s83, v143, 62
	v_readlane_b32 s84, v145, 62
	v_mul_f32_e32 v154, s88, v126
	v_fmac_f32_e32 v146, s77, v154
	v_fmac_f32_e32 v147, s78, v154
	v_fmac_f32_e32 v148, s79, v154
	v_fmac_f32_e32 v149, s80, v154
	v_fmac_f32_e32 v150, s81, v154
	v_fmac_f32_e32 v151, s82, v154
	v_fmac_f32_e32 v152, s83, v154
	v_fmac_f32_e32 v153, s84, v154
	v_readlane_b32 s88, v129, 63
	v_readlane_b32 s77, v131, 63
	v_readlane_b32 s78, v133, 63
	v_readlane_b32 s79, v135, 63
	v_readlane_b32 s80, v137, 63
	v_readlane_b32 s81, v139, 63
	v_readlane_b32 s82, v141, 63
	v_readlane_b32 s83, v143, 63
	v_readlane_b32 s84, v145, 63
	v_mul_f32_e32 v154, s88, v127
	v_fmac_f32_e32 v146, s77, v154
	v_fmac_f32_e32 v147, s78, v154
	v_fmac_f32_e32 v148, s79, v154
	v_fmac_f32_e32 v149, s80, v154
	v_fmac_f32_e32 v150, s81, v154
	v_fmac_f32_e32 v151, s82, v154
	v_fmac_f32_e32 v152, s83, v154
	v_fmac_f32_e32 v153, s84, v154
	v_cvt_pk_bf16_f32 v72, v146, v147
	v_cvt_pk_bf16_f32 v73, v148, v149
	v_cvt_pk_bf16_f32 v74, v150, v151
	v_cvt_pk_bf16_f32 v75, v152, v153
	s_lshl_b32 s79, s27, 1
	s_add_u32 s86, s18, 0x900000
	s_addc_u32 s87, s19, 0
	s_add_u32 s86, s86, s79
	s_addc_u32 s87, s87, 0
	v_lshlrev_b32_e32 v158, 11, v155
	global_store_dwordx4 v158, v[72:75], s[86:87] sc1
